# first mainloop iteration peeled in 9 GEMM instances with SrcC=0 on the first MFMA of each accumulator; per-unit accumulator zeroing (128 v_mov) removed
# speedup vs baseline: 1.0322x; 1.0056x over previous
.LBB7_325:
	s_add_u32 s34, s62, s77
	s_addc_u32 s35, s63, s52
	s_add_u32 s36, s62, s30
	s_addc_u32 s37, s63, s31
	s_andn2_b64 vcc, exec, s[14:15]
	s_cbranch_vccnz .LBB7_337
	s_and_b64 s[42:43], s[6:7], exec
	s_cselect_b32 s81, s35, s39
	s_cselect_b32 s82, s34, s38
	s_cselect_b32 s83, s37, s41
	s_cselect_b32 s84, s36, s40
	s_add_u32 s38, s38, 0x40080
	s_addc_u32 s39, s39, 0
	s_add_u32 s85, s40, 0x100
	s_addc_u32 s86, s41, 0
	s_mov_b32 s40, 0
	s_waitcnt vmcnt(0)
.Lpeel_327:
	ds_read_b128 v[128:131], v177
	ds_read_b128 v[132:135], v177 offset:1024
	ds_read_b128 v[136:139], v177 offset:2048
	ds_read_b128 v[140:143], v177 offset:3072
	ds_read_b128 v[160:163], v178
	ds_read_b128 v[164:167], v178 offset:1024
	ds_read_b128 v[168:171], v178 offset:2048
	ds_read_b128 v[180:183], v178 offset:3072
	s_add_i32 s87, s40, 2
	s_add_u32 s41, s38, 0xfffc0080
	s_addc_u32 s42, s39, -1
	s_cmp_eq_u32 s57, s40
	s_cselect_b32 s40, s84, s85
	s_cselect_b32 s43, s81, s42
	s_cselect_b32 s42, s82, s41
	s_cselect_b32 s41, s83, s86
	s_add_i32 m0, s48, 0xc000
	ds_read_b128 v[184:187], v179
	ds_read_b128 v[188:191], v179 offset:1024
	ds_read_b128 v[192:195], v179 offset:2048
	ds_read_b128 v[196:199], v179 offset:3072
	ds_read_b128 v[202:205], v179 offset:4096
	ds_read_b128 v[206:209], v179 offset:5120
	ds_read_b128 v[210:213], v179 offset:6144
	ds_read_b128 v[214:217], v179 offset:7168
	global_load_lds_dwordx4 v152, s[38:39]
	s_add_i32 m0, s48, 0xe000
	s_nop 0
	global_load_lds_dwordx4 v154, s[38:39]
	s_waitcnt vmcnt(8)
	s_waitcnt lgkmcnt(0)
	s_setprio 1
	s_barrier
	v_mfma_f32_16x16x32_bf16 v[124:127], v[128:131], v[184:187], 0
	v_mfma_f32_16x16x32_bf16 v[120:123], v[136:139], v[184:187], 0
	v_mfma_f32_16x16x32_bf16 v[108:111], v[128:131], v[192:195], 0
	v_mfma_f32_16x16x32_bf16 v[104:107], v[136:139], v[192:195], 0
	v_mfma_f32_16x16x32_bf16 v[92:95], v[128:131], v[202:205], 0
	v_mfma_f32_16x16x32_bf16 v[88:91], v[136:139], v[202:205], 0
	v_mfma_f32_16x16x32_bf16 v[76:79], v[128:131], v[210:213], 0
	v_mfma_f32_16x16x32_bf16 v[72:75], v[136:139], v[210:213], 0
	v_mfma_f32_16x16x32_bf16 v[124:127], v[132:135], v[188:191], v[124:127]
	v_mfma_f32_16x16x32_bf16 v[120:123], v[140:143], v[188:191], v[120:123]
	v_mfma_f32_16x16x32_bf16 v[108:111], v[132:135], v[196:199], v[108:111]
	v_mfma_f32_16x16x32_bf16 v[104:107], v[140:143], v[196:199], v[104:107]
	v_mfma_f32_16x16x32_bf16 v[92:95], v[132:135], v[206:209], v[92:95]
	v_mfma_f32_16x16x32_bf16 v[88:91], v[140:143], v[206:209], v[88:91]
	v_mfma_f32_16x16x32_bf16 v[76:79], v[132:135], v[214:217], v[76:79]
	v_mfma_f32_16x16x32_bf16 v[72:75], v[140:143], v[214:217], v[72:75]
	v_mfma_f32_16x16x32_bf16 v[116:119], v[160:163], v[184:187], 0
	v_mfma_f32_16x16x32_bf16 v[112:115], v[168:171], v[184:187], 0
	v_mfma_f32_16x16x32_bf16 v[100:103], v[160:163], v[192:195], 0
	v_mfma_f32_16x16x32_bf16 v[96:99], v[168:171], v[192:195], 0
	v_mfma_f32_16x16x32_bf16 v[84:87], v[160:163], v[202:205], 0
	v_mfma_f32_16x16x32_bf16 v[80:83], v[168:171], v[202:205], 0
	v_mfma_f32_16x16x32_bf16 v[68:71], v[160:163], v[210:213], 0
	v_mfma_f32_16x16x32_bf16 v[64:67], v[168:171], v[210:213], 0
	v_mfma_f32_16x16x32_bf16 v[116:119], v[164:167], v[188:191], v[116:119]
	v_mfma_f32_16x16x32_bf16 v[112:115], v[180:183], v[188:191], v[112:115]
	v_mfma_f32_16x16x32_bf16 v[100:103], v[164:167], v[196:199], v[100:103]
	v_mfma_f32_16x16x32_bf16 v[96:99], v[180:183], v[196:199], v[96:99]
	v_mfma_f32_16x16x32_bf16 v[84:87], v[164:167], v[206:209], v[84:87]
	v_mfma_f32_16x16x32_bf16 v[80:83], v[180:183], v[206:209], v[80:83]
	v_mfma_f32_16x16x32_bf16 v[68:71], v[164:167], v[214:217], v[68:71]
	v_mfma_f32_16x16x32_bf16 v[64:67], v[180:183], v[214:217], v[64:67]
	s_barrier
	s_setprio 0
	s_add_i32 s88, s58, s33
	v_lshl_add_u64 v[172:173], s[40:41], 0, v[148:149]
	s_mov_b32 m0, s88
	ds_read_b128 v[184:187], v179 offset:16384
	ds_read_b128 v[188:191], v179 offset:17408
	ds_read_b128 v[192:195], v179 offset:18432
	ds_read_b128 v[196:199], v179 offset:19456
	ds_read_b128 v[202:205], v179 offset:20480
	ds_read_b128 v[206:209], v179 offset:21504
	ds_read_b128 v[210:213], v179 offset:22528
	ds_read_b128 v[214:217], v179 offset:23552
	global_load_lds_dwordx4 v[172:173], off
	s_add_i32 m0, s88, 0x2000
	s_add_u32 s88, s40, 0x40000
	v_lshl_add_u64 v[218:219], s[40:41], 0, v[144:145]
	s_addc_u32 s89, s41, 0
	s_add_i32 s90, s64, s33
	global_load_lds_dwordx4 v[218:219], off
	s_mov_b32 m0, s90
	v_lshl_add_u64 v[222:223], s[42:43], 0, v[146:147]
	global_load_lds_dwordx4 v148, s[88:89]
	s_add_i32 m0, s90, 0x2000
	s_nop 0
	global_load_lds_dwordx4 v144, s[88:89]
	v_lshl_add_u64 v[220:221], s[42:43], 0, v[150:151]
	s_mov_b32 m0, s48
	s_nop 0
	global_load_lds_dwordx4 v[220:221], off
	s_mov_b32 m0, s49
	s_nop 0
	global_load_lds_dwordx4 v[222:223], off
	s_waitcnt vmcnt(8)
	s_waitcnt lgkmcnt(0)
	s_setprio 1
	s_barrier
	v_mfma_f32_16x16x32_bf16 v[60:63], v[128:131], v[184:187], 0
	v_mfma_f32_16x16x32_bf16 v[56:59], v[136:139], v[184:187], 0
	v_mfma_f32_16x16x32_bf16 v[44:47], v[128:131], v[192:195], 0
	v_mfma_f32_16x16x32_bf16 v[40:43], v[136:139], v[192:195], 0
	v_mfma_f32_16x16x32_bf16 v[28:31], v[128:131], v[202:205], 0
	v_mfma_f32_16x16x32_bf16 v[24:27], v[136:139], v[202:205], 0
	v_mfma_f32_16x16x32_bf16 v[12:15], v[128:131], v[210:213], 0
	v_mfma_f32_16x16x32_bf16 v[8:11], v[136:139], v[210:213], 0
	v_mfma_f32_16x16x32_bf16 v[60:63], v[132:135], v[188:191], v[60:63]
	v_mfma_f32_16x16x32_bf16 v[56:59], v[140:143], v[188:191], v[56:59]
	v_mfma_f32_16x16x32_bf16 v[44:47], v[132:135], v[196:199], v[44:47]
	v_mfma_f32_16x16x32_bf16 v[40:43], v[140:143], v[196:199], v[40:43]
	v_mfma_f32_16x16x32_bf16 v[28:31], v[132:135], v[206:209], v[28:31]
	v_mfma_f32_16x16x32_bf16 v[24:27], v[140:143], v[206:209], v[24:27]
	v_mfma_f32_16x16x32_bf16 v[12:15], v[132:135], v[214:217], v[12:15]
	v_mfma_f32_16x16x32_bf16 v[8:11], v[140:143], v[214:217], v[8:11]
	v_mfma_f32_16x16x32_bf16 v[52:55], v[160:163], v[184:187], 0
	v_mfma_f32_16x16x32_bf16 v[48:51], v[168:171], v[184:187], 0
	v_mfma_f32_16x16x32_bf16 v[36:39], v[160:163], v[192:195], 0
	v_mfma_f32_16x16x32_bf16 v[32:35], v[168:171], v[192:195], 0
	v_mfma_f32_16x16x32_bf16 v[20:23], v[160:163], v[202:205], 0
	v_mfma_f32_16x16x32_bf16 v[16:19], v[168:171], v[202:205], 0
	v_mfma_f32_16x16x32_bf16 v[4:7], v[160:163], v[210:213], 0
	v_mfma_f32_16x16x32_bf16 v[0:3], v[168:171], v[210:213], 0
	v_mfma_f32_16x16x32_bf16 v[52:55], v[164:167], v[188:191], v[52:55]
	v_mfma_f32_16x16x32_bf16 v[48:51], v[180:183], v[188:191], v[48:51]
	v_mfma_f32_16x16x32_bf16 v[36:39], v[164:167], v[196:199], v[36:39]
	v_mfma_f32_16x16x32_bf16 v[32:35], v[180:183], v[196:199], v[32:35]
	v_mfma_f32_16x16x32_bf16 v[20:23], v[164:167], v[206:209], v[20:23]
	v_mfma_f32_16x16x32_bf16 v[16:19], v[180:183], v[206:209], v[16:19]
	v_mfma_f32_16x16x32_bf16 v[4:7], v[164:167], v[214:217], v[4:7]
	v_mfma_f32_16x16x32_bf16 v[0:3], v[180:183], v[214:217], v[0:3]
	s_barrier
	s_setprio 0
	s_add_i32 s88, 0, 0x18000
	s_add_i32 s89, 0, 0x1c000
	v_add_u32_e32 v140, s88, v175
	v_add_u32_e32 v180, s89, v175
	ds_read_b128 v[128:131], v140
	ds_read_b128 v[132:135], v140 offset:1024
	ds_read_b128 v[136:139], v140 offset:2048
	ds_read_b128 v[140:143], v140 offset:3072
	ds_read_b128 v[160:163], v180
	ds_read_b128 v[164:167], v180 offset:1024
	ds_read_b128 v[168:171], v180 offset:2048
	ds_read_b128 v[180:183], v180 offset:3072
	s_add_u32 s42, s42, 0x40000
	s_addc_u32 s43, s43, 0
	s_mov_b32 m0, s50
	ds_read_b128 v[184:187], v179 offset:32768
	ds_read_b128 v[188:191], v179 offset:33792
	ds_read_b128 v[192:195], v179 offset:34816
	ds_read_b128 v[196:199], v179 offset:35840
	ds_read_b128 v[202:205], v179 offset:36864
	ds_read_b128 v[206:209], v179 offset:37888
	ds_read_b128 v[210:213], v179 offset:38912
	ds_read_b128 v[214:217], v179 offset:39936
	global_load_lds_dwordx4 v150, s[42:43]
	s_mov_b32 m0, s51
	s_nop 0
	global_load_lds_dwordx4 v146, s[42:43]
	s_waitcnt vmcnt(8)
	s_waitcnt lgkmcnt(0)
	s_setprio 1
	s_barrier
	v_mfma_f32_16x16x32_bf16 v[124:127], v[128:131], v[184:187], v[124:127]
	v_mfma_f32_16x16x32_bf16 v[120:123], v[136:139], v[184:187], v[120:123]
	v_mfma_f32_16x16x32_bf16 v[108:111], v[128:131], v[192:195], v[108:111]
	v_mfma_f32_16x16x32_bf16 v[104:107], v[136:139], v[192:195], v[104:107]
	v_mfma_f32_16x16x32_bf16 v[92:95], v[128:131], v[202:205], v[92:95]
	v_mfma_f32_16x16x32_bf16 v[88:91], v[136:139], v[202:205], v[88:91]
	v_mfma_f32_16x16x32_bf16 v[76:79], v[128:131], v[210:213], v[76:79]
	v_mfma_f32_16x16x32_bf16 v[72:75], v[136:139], v[210:213], v[72:75]
	v_mfma_f32_16x16x32_bf16 v[124:127], v[132:135], v[188:191], v[124:127]
	v_mfma_f32_16x16x32_bf16 v[120:123], v[140:143], v[188:191], v[120:123]
	v_mfma_f32_16x16x32_bf16 v[108:111], v[132:135], v[196:199], v[108:111]
	v_mfma_f32_16x16x32_bf16 v[104:107], v[140:143], v[196:199], v[104:107]
	v_mfma_f32_16x16x32_bf16 v[92:95], v[132:135], v[206:209], v[92:95]
	v_mfma_f32_16x16x32_bf16 v[88:91], v[140:143], v[206:209], v[88:91]
	v_mfma_f32_16x16x32_bf16 v[76:79], v[132:135], v[214:217], v[76:79]
	v_mfma_f32_16x16x32_bf16 v[72:75], v[140:143], v[214:217], v[72:75]
	v_mfma_f32_16x16x32_bf16 v[116:119], v[160:163], v[184:187], v[116:119]
	v_mfma_f32_16x16x32_bf16 v[112:115], v[168:171], v[184:187], v[112:115]
	v_mfma_f32_16x16x32_bf16 v[100:103], v[160:163], v[192:195], v[100:103]
	v_mfma_f32_16x16x32_bf16 v[96:99], v[168:171], v[192:195], v[96:99]
	v_mfma_f32_16x16x32_bf16 v[84:87], v[160:163], v[202:205], v[84:87]
	v_mfma_f32_16x16x32_bf16 v[80:83], v[168:171], v[202:205], v[80:83]
	v_mfma_f32_16x16x32_bf16 v[68:71], v[160:163], v[210:213], v[68:71]
	v_mfma_f32_16x16x32_bf16 v[64:67], v[168:171], v[210:213], v[64:67]
	v_mfma_f32_16x16x32_bf16 v[116:119], v[164:167], v[188:191], v[116:119]
	v_mfma_f32_16x16x32_bf16 v[112:115], v[180:183], v[188:191], v[112:115]
	v_mfma_f32_16x16x32_bf16 v[100:103], v[164:167], v[196:199], v[100:103]
	v_mfma_f32_16x16x32_bf16 v[96:99], v[180:183], v[196:199], v[96:99]
	v_mfma_f32_16x16x32_bf16 v[84:87], v[164:167], v[206:209], v[84:87]
	v_mfma_f32_16x16x32_bf16 v[80:83], v[180:183], v[206:209], v[80:83]
	v_mfma_f32_16x16x32_bf16 v[68:71], v[164:167], v[214:217], v[68:71]
	v_mfma_f32_16x16x32_bf16 v[64:67], v[180:183], v[214:217], v[64:67]
	s_barrier
	s_setprio 0
	s_add_i32 s42, s88, s33
	v_lshl_add_u64 v[172:173], v[172:173], 0, s[10:11]
	s_mov_b32 m0, s42
	ds_read_b128 v[184:187], v179 offset:49152
	ds_read_b128 v[188:191], v179 offset:50176
	ds_read_b128 v[192:195], v179 offset:51200
	ds_read_b128 v[196:199], v179 offset:52224
	ds_read_b128 v[202:205], v179 offset:53248
	ds_read_b128 v[206:209], v179 offset:54272
	ds_read_b128 v[210:213], v179 offset:55296
	ds_read_b128 v[214:217], v179 offset:56320
	global_load_lds_dwordx4 v[172:173], off
	s_add_i32 m0, s42, 0x2000
	s_add_u32 s40, s40, 0x40080
	v_lshl_add_u64 v[172:173], v[218:219], 0, s[10:11]
	s_addc_u32 s41, s41, 0
	s_add_i32 s42, s89, s33
	global_load_lds_dwordx4 v[172:173], off
	s_mov_b32 m0, s42
	s_nop 0
	global_load_lds_dwordx4 v148, s[40:41]
	s_add_i32 m0, s42, 0x2000
	s_nop 0
	global_load_lds_dwordx4 v144, s[40:41]
	v_lshl_add_u64 v[172:173], v[220:221], 0, s[10:11]
	s_mov_b32 m0, s55
	s_nop 0
	global_load_lds_dwordx4 v[172:173], off
	v_lshl_add_u64 v[172:173], v[222:223], 0, s[10:11]
	s_mov_b32 m0, s56
	s_nop 0
	global_load_lds_dwordx4 v[172:173], off
	s_waitcnt vmcnt(8)
	s_waitcnt lgkmcnt(0)
	s_setprio 1
	s_barrier
	v_mfma_f32_16x16x32_bf16 v[60:63], v[128:131], v[184:187], v[60:63]
	v_mfma_f32_16x16x32_bf16 v[56:59], v[136:139], v[184:187], v[56:59]
	v_mfma_f32_16x16x32_bf16 v[44:47], v[128:131], v[192:195], v[44:47]
	v_mfma_f32_16x16x32_bf16 v[40:43], v[136:139], v[192:195], v[40:43]
	v_mfma_f32_16x16x32_bf16 v[28:31], v[128:131], v[202:205], v[28:31]
	v_mfma_f32_16x16x32_bf16 v[24:27], v[136:139], v[202:205], v[24:27]
	v_mfma_f32_16x16x32_bf16 v[12:15], v[128:131], v[210:213], v[12:15]
	v_mfma_f32_16x16x32_bf16 v[8:11], v[136:139], v[210:213], v[8:11]
	v_mfma_f32_16x16x32_bf16 v[60:63], v[132:135], v[188:191], v[60:63]
	v_mfma_f32_16x16x32_bf16 v[56:59], v[140:143], v[188:191], v[56:59]
	v_mfma_f32_16x16x32_bf16 v[44:47], v[132:135], v[196:199], v[44:47]
	v_mfma_f32_16x16x32_bf16 v[40:43], v[140:143], v[196:199], v[40:43]
	v_mfma_f32_16x16x32_bf16 v[28:31], v[132:135], v[206:209], v[28:31]
	v_mfma_f32_16x16x32_bf16 v[24:27], v[140:143], v[206:209], v[24:27]
	v_mfma_f32_16x16x32_bf16 v[12:15], v[132:135], v[214:217], v[12:15]
	v_mfma_f32_16x16x32_bf16 v[8:11], v[140:143], v[214:217], v[8:11]
	v_mfma_f32_16x16x32_bf16 v[52:55], v[160:163], v[184:187], v[52:55]
	v_mfma_f32_16x16x32_bf16 v[48:51], v[168:171], v[184:187], v[48:51]
	v_mfma_f32_16x16x32_bf16 v[36:39], v[160:163], v[192:195], v[36:39]
	v_mfma_f32_16x16x32_bf16 v[32:35], v[168:171], v[192:195], v[32:35]
	v_mfma_f32_16x16x32_bf16 v[20:23], v[160:163], v[202:205], v[20:23]
	v_mfma_f32_16x16x32_bf16 v[16:19], v[168:171], v[202:205], v[16:19]
	v_mfma_f32_16x16x32_bf16 v[4:7], v[160:163], v[210:213], v[4:7]
	v_mfma_f32_16x16x32_bf16 v[0:3], v[168:171], v[210:213], v[0:3]
	v_mfma_f32_16x16x32_bf16 v[52:55], v[164:167], v[188:191], v[52:55]
	v_mfma_f32_16x16x32_bf16 v[48:51], v[180:183], v[188:191], v[48:51]
	v_mfma_f32_16x16x32_bf16 v[36:39], v[164:167], v[196:199], v[36:39]
	v_mfma_f32_16x16x32_bf16 v[32:35], v[180:183], v[196:199], v[32:35]
	v_mfma_f32_16x16x32_bf16 v[20:23], v[164:167], v[206:209], v[20:23]
	v_mfma_f32_16x16x32_bf16 v[16:19], v[180:183], v[206:209], v[16:19]
	v_mfma_f32_16x16x32_bf16 v[4:7], v[164:167], v[214:217], v[4:7]
	v_mfma_f32_16x16x32_bf16 v[0:3], v[180:183], v[214:217], v[0:3]
	s_barrier
	s_setprio 0
	s_add_u32 s38, s38, 0x100
	s_addc_u32 s39, s39, 0
	s_add_u32 s85, s85, 0x100
	s_addc_u32 s86, s86, 0
	s_cmp_ge_i32 s87, s26
	s_mov_b32 s40, s87
	s_cbranch_scc0 .LBB7_327
	s_branch .Lpeelx_327

.Lpeelx_327:
	v_readlane_b32 s87, v251, 12
	v_readlane_b32 s89, v251, 13
	s_and_b64 vcc, exec, s[12:13]
	s_cbranch_vccz .LBB7_330

.LBB7_355:
	s_add_u32 s0, s68, s14
	s_addc_u32 s1, s69, s15
	s_add_u32 s6, s85, s18
	s_addc_u32 s7, s31, s19
	s_andn2_b64 vcc, exec, s[54:55]
	s_cbranch_vccnz .LBB7_363
	s_and_b64 s[28:29], s[40:41], exec
	s_cselect_b32 s9, s1, s17
	s_cselect_b32 s13, s0, s16
	s_cselect_b32 s28, s7, s43
	s_cselect_b32 s39, s6, s42
	s_add_u32 s16, s16, 0x40080
	s_addc_u32 s17, s17, 0
	s_add_u32 s56, s42, 0x100
	s_addc_u32 s57, s43, 0
	s_mov_b32 s42, 0
	s_cmp_lt_u32 s22, 2
	s_cbranch_scc1 .Lswi_nobar
	s_andn2_b64 vcc, exec, s[50:51]
	s_cbranch_vccnz .Lswi_nobar
	s_barrier
.Lswi_nobar:
.Lpeel_357:
	s_add_i32 s86, s42, 2
	s_add_u32 s29, s16, 0xfffc0080
	s_addc_u32 s37, s17, -1
	s_add_i32 s74, 0, 0x10000
	s_cmp_eq_u32 s20, s42
	s_cselect_b32 s73, s9, s37
	s_cselect_b32 s72, s13, s29
	v_add_u32_e32 v170, s74, v179
	s_cselect_b32 s43, s28, s57
	s_cselect_b32 s42, s39, s56
	s_add_i32 s29, 0, 0x14000
	ds_read_b128 v[130:133], v170
	ds_read_b128 v[180:183], v170 offset:1024
	ds_read_b128 v[184:187], v170 offset:2048
	ds_read_b128 v[188:191], v170 offset:3072
	v_add_u32_e32 v170, s29, v179
	ds_read_b128 v[192:195], v170
	ds_read_b128 v[196:199], v170 offset:1024
	ds_read_b128 v[204:207], v170 offset:2048
	ds_read_b128 v[208:211], v170 offset:3072
	s_add_i32 m0, s4, 0xc000
	ds_read_b128 v[212:215], v143
	ds_read_b128 v[216:219], v143 offset:1024
	ds_read_b128 v[220:223], v143 offset:2048
	ds_read_b128 v[224:227], v143 offset:3072
	ds_read_b128 v[228:231], v143 offset:4096
	ds_read_b128 v[232:235], v143 offset:5120
	ds_read_b128 v[236:239], v143 offset:6144
	ds_read_b128 v[240:243], v143 offset:7168
	global_load_lds_dwordx4 v174, s[16:17]
	s_add_i32 m0, s4, 0xe000
	s_nop 0
	global_load_lds_dwordx4 v176, s[16:17]
	s_waitcnt vmcnt(8)
	s_waitcnt lgkmcnt(0)
	s_setprio 1
	s_barrier
	v_mfma_f32_16x16x32_bf16 v[126:129], v[130:133], v[212:215], 0
	v_mfma_f32_16x16x32_bf16 v[118:121], v[184:187], v[212:215], 0
	v_mfma_f32_16x16x32_bf16 v[110:113], v[130:133], v[220:223], 0
	v_mfma_f32_16x16x32_bf16 v[102:105], v[184:187], v[220:223], 0
	v_mfma_f32_16x16x32_bf16 v[94:97], v[130:133], v[228:231], 0
	v_mfma_f32_16x16x32_bf16 v[86:89], v[184:187], v[228:231], 0
	v_mfma_f32_16x16x32_bf16 v[78:81], v[130:133], v[236:239], 0
	v_mfma_f32_16x16x32_bf16 v[70:73], v[184:187], v[236:239], 0
	v_mfma_f32_16x16x32_bf16 v[126:129], v[180:183], v[216:219], v[126:129]
	v_mfma_f32_16x16x32_bf16 v[118:121], v[188:191], v[216:219], v[118:121]
	v_mfma_f32_16x16x32_bf16 v[110:113], v[180:183], v[224:227], v[110:113]
	v_mfma_f32_16x16x32_bf16 v[102:105], v[188:191], v[224:227], v[102:105]
	v_mfma_f32_16x16x32_bf16 v[94:97], v[180:183], v[232:235], v[94:97]
	v_mfma_f32_16x16x32_bf16 v[86:89], v[188:191], v[232:235], v[86:89]
	v_mfma_f32_16x16x32_bf16 v[78:81], v[180:183], v[240:243], v[78:81]
	v_mfma_f32_16x16x32_bf16 v[70:73], v[188:191], v[240:243], v[70:73]
	v_mfma_f32_16x16x32_bf16 v[122:125], v[192:195], v[212:215], 0
	v_mfma_f32_16x16x32_bf16 v[114:117], v[204:207], v[212:215], 0
	v_mfma_f32_16x16x32_bf16 v[106:109], v[192:195], v[220:223], 0
	v_mfma_f32_16x16x32_bf16 v[98:101], v[204:207], v[220:223], 0
	v_mfma_f32_16x16x32_bf16 v[90:93], v[192:195], v[228:231], 0
	v_mfma_f32_16x16x32_bf16 v[82:85], v[204:207], v[228:231], 0
	v_mfma_f32_16x16x32_bf16 v[74:77], v[192:195], v[236:239], 0
	v_mfma_f32_16x16x32_bf16 v[66:69], v[204:207], v[236:239], 0
	v_mfma_f32_16x16x32_bf16 v[122:125], v[196:199], v[216:219], v[122:125]
	v_mfma_f32_16x16x32_bf16 v[114:117], v[208:211], v[216:219], v[114:117]
	v_mfma_f32_16x16x32_bf16 v[106:109], v[196:199], v[224:227], v[106:109]
	v_mfma_f32_16x16x32_bf16 v[98:101], v[208:211], v[224:227], v[98:101]
	v_mfma_f32_16x16x32_bf16 v[90:93], v[196:199], v[232:235], v[90:93]
	v_mfma_f32_16x16x32_bf16 v[82:85], v[208:211], v[232:235], v[82:85]
	v_mfma_f32_16x16x32_bf16 v[74:77], v[196:199], v[240:243], v[74:77]
	v_mfma_f32_16x16x32_bf16 v[66:69], v[208:211], v[240:243], v[66:69]
	s_barrier
	s_setprio 0
	s_add_i32 s37, s74, s84
	v_lshl_add_u64 v[244:245], s[42:43], 0, v[138:139]
	s_mov_b32 m0, s37
	ds_read_b128 v[212:215], v143 offset:16384
	ds_read_b128 v[216:219], v143 offset:17408
	ds_read_b128 v[220:223], v143 offset:18432
	ds_read_b128 v[224:227], v143 offset:19456
	ds_read_b128 v[228:231], v143 offset:20480
	ds_read_b128 v[232:235], v143 offset:21504
	ds_read_b128 v[236:239], v143 offset:22528
	ds_read_b128 v[240:243], v143 offset:23552
	global_load_lds_dwordx4 v[244:245], off
	s_add_i32 m0, s37, 0x2000
	s_add_u32 s74, s42, 0x40000
	v_lshl_add_u64 v[246:247], s[42:43], 0, v[134:135]
	s_addc_u32 s75, s43, 0
	s_add_i32 s29, s29, s84
	global_load_lds_dwordx4 v[246:247], off
	s_mov_b32 m0, s29
	v_lshl_add_u64 v[170:171], s[72:73], 0, v[136:137]
	global_load_lds_dwordx4 v138, s[74:75]
	s_add_i32 m0, s29, 0x2000
	s_nop 0
	global_load_lds_dwordx4 v134, s[74:75]
	v_lshl_add_u64 v[248:249], s[72:73], 0, v[140:141]
	s_mov_b32 m0, s4
	s_nop 0
	global_load_lds_dwordx4 v[248:249], off
	s_mov_b32 m0, s5
	s_nop 0
	global_load_lds_dwordx4 v[170:171], off
	s_waitcnt vmcnt(8)
	s_waitcnt lgkmcnt(0)
	s_setprio 1
	s_barrier
	v_mfma_f32_16x16x32_bf16 v[62:65], v[130:133], v[212:215], 0
	v_mfma_f32_16x16x32_bf16 v[54:57], v[184:187], v[212:215], 0
	v_mfma_f32_16x16x32_bf16 v[46:49], v[130:133], v[220:223], 0
	v_mfma_f32_16x16x32_bf16 v[38:41], v[184:187], v[220:223], 0
	v_mfma_f32_16x16x32_bf16 v[30:33], v[130:133], v[228:231], 0
	v_mfma_f32_16x16x32_bf16 v[22:25], v[184:187], v[228:231], 0
	v_mfma_f32_16x16x32_bf16 v[14:17], v[130:133], v[236:239], 0
	v_mfma_f32_16x16x32_bf16 v[6:9], v[184:187], v[236:239], 0
	v_mfma_f32_16x16x32_bf16 v[62:65], v[180:183], v[216:219], v[62:65]
	v_mfma_f32_16x16x32_bf16 v[54:57], v[188:191], v[216:219], v[54:57]
	v_mfma_f32_16x16x32_bf16 v[46:49], v[180:183], v[224:227], v[46:49]
	v_mfma_f32_16x16x32_bf16 v[38:41], v[188:191], v[224:227], v[38:41]
	v_mfma_f32_16x16x32_bf16 v[30:33], v[180:183], v[232:235], v[30:33]
	v_mfma_f32_16x16x32_bf16 v[22:25], v[188:191], v[232:235], v[22:25]
	v_mfma_f32_16x16x32_bf16 v[14:17], v[180:183], v[240:243], v[14:17]
	v_mfma_f32_16x16x32_bf16 v[6:9], v[188:191], v[240:243], v[6:9]
	v_mfma_f32_16x16x32_bf16 v[58:61], v[192:195], v[212:215], 0
	v_mfma_f32_16x16x32_bf16 v[50:53], v[204:207], v[212:215], 0
	v_mfma_f32_16x16x32_bf16 v[42:45], v[192:195], v[220:223], 0
	v_mfma_f32_16x16x32_bf16 v[34:37], v[204:207], v[220:223], 0
	v_mfma_f32_16x16x32_bf16 v[26:29], v[192:195], v[228:231], 0
	v_mfma_f32_16x16x32_bf16 v[18:21], v[204:207], v[228:231], 0
	v_mfma_f32_16x16x32_bf16 v[10:13], v[192:195], v[236:239], 0
	v_mfma_f32_16x16x32_bf16 v[2:5], v[204:207], v[236:239], 0
	v_mfma_f32_16x16x32_bf16 v[58:61], v[196:199], v[216:219], v[58:61]
	v_mfma_f32_16x16x32_bf16 v[50:53], v[208:211], v[216:219], v[50:53]
	v_mfma_f32_16x16x32_bf16 v[42:45], v[196:199], v[224:227], v[42:45]
	v_mfma_f32_16x16x32_bf16 v[34:37], v[208:211], v[224:227], v[34:37]
	v_mfma_f32_16x16x32_bf16 v[26:29], v[196:199], v[232:235], v[26:29]
	v_mfma_f32_16x16x32_bf16 v[18:21], v[208:211], v[232:235], v[18:21]
	v_mfma_f32_16x16x32_bf16 v[10:13], v[196:199], v[240:243], v[10:13]
	v_mfma_f32_16x16x32_bf16 v[2:5], v[208:211], v[240:243], v[2:5]
	s_barrier
	s_setprio 0
	s_add_i32 s29, 0, 0x18000
	v_add_u32_e32 v172, s29, v179
	s_add_i32 s37, 0, 0x1c000
	ds_read_b128 v[130:133], v172
	ds_read_b128 v[180:183], v172 offset:1024
	ds_read_b128 v[184:187], v172 offset:2048
	ds_read_b128 v[188:191], v172 offset:3072
	v_add_u32_e32 v172, s37, v179
	ds_read_b128 v[192:195], v172
	ds_read_b128 v[196:199], v172 offset:1024
	ds_read_b128 v[204:207], v172 offset:2048
	ds_read_b128 v[208:211], v172 offset:3072
	s_add_u32 s72, s72, 0x40000
	s_addc_u32 s73, s73, 0
	s_mov_b32 m0, s93
	ds_read_b128 v[212:215], v143 offset:32768
	ds_read_b128 v[216:219], v143 offset:33792
	ds_read_b128 v[220:223], v143 offset:34816
	ds_read_b128 v[224:227], v143 offset:35840
	ds_read_b128 v[228:231], v143 offset:36864
	ds_read_b128 v[232:235], v143 offset:37888
	ds_read_b128 v[236:239], v143 offset:38912
	ds_read_b128 v[240:243], v143 offset:39936
	global_load_lds_dwordx4 v140, s[72:73]
	s_mov_b32 m0, s33
	s_nop 0
	global_load_lds_dwordx4 v136, s[72:73]
	s_waitcnt vmcnt(8)
	s_waitcnt lgkmcnt(0)
	s_setprio 1
	s_barrier
	v_mfma_f32_16x16x32_bf16 v[126:129], v[130:133], v[212:215], v[126:129]
	v_mfma_f32_16x16x32_bf16 v[118:121], v[184:187], v[212:215], v[118:121]
	v_mfma_f32_16x16x32_bf16 v[110:113], v[130:133], v[220:223], v[110:113]
	v_mfma_f32_16x16x32_bf16 v[102:105], v[184:187], v[220:223], v[102:105]
	v_mfma_f32_16x16x32_bf16 v[94:97], v[130:133], v[228:231], v[94:97]
	v_mfma_f32_16x16x32_bf16 v[86:89], v[184:187], v[228:231], v[86:89]
	v_mfma_f32_16x16x32_bf16 v[78:81], v[130:133], v[236:239], v[78:81]
	v_mfma_f32_16x16x32_bf16 v[70:73], v[184:187], v[236:239], v[70:73]
	v_mfma_f32_16x16x32_bf16 v[126:129], v[180:183], v[216:219], v[126:129]
	v_mfma_f32_16x16x32_bf16 v[118:121], v[188:191], v[216:219], v[118:121]
	v_mfma_f32_16x16x32_bf16 v[110:113], v[180:183], v[224:227], v[110:113]
	v_mfma_f32_16x16x32_bf16 v[102:105], v[188:191], v[224:227], v[102:105]
	v_mfma_f32_16x16x32_bf16 v[94:97], v[180:183], v[232:235], v[94:97]
	v_mfma_f32_16x16x32_bf16 v[86:89], v[188:191], v[232:235], v[86:89]
	v_mfma_f32_16x16x32_bf16 v[78:81], v[180:183], v[240:243], v[78:81]
	v_mfma_f32_16x16x32_bf16 v[70:73], v[188:191], v[240:243], v[70:73]
	v_mfma_f32_16x16x32_bf16 v[122:125], v[192:195], v[212:215], v[122:125]
	v_mfma_f32_16x16x32_bf16 v[114:117], v[204:207], v[212:215], v[114:117]
	v_mfma_f32_16x16x32_bf16 v[106:109], v[192:195], v[220:223], v[106:109]
	v_mfma_f32_16x16x32_bf16 v[98:101], v[204:207], v[220:223], v[98:101]
	v_mfma_f32_16x16x32_bf16 v[90:93], v[192:195], v[228:231], v[90:93]
	v_mfma_f32_16x16x32_bf16 v[82:85], v[204:207], v[228:231], v[82:85]
	v_mfma_f32_16x16x32_bf16 v[74:77], v[192:195], v[236:239], v[74:77]
	v_mfma_f32_16x16x32_bf16 v[66:69], v[204:207], v[236:239], v[66:69]
	v_mfma_f32_16x16x32_bf16 v[122:125], v[196:199], v[216:219], v[122:125]
	v_mfma_f32_16x16x32_bf16 v[114:117], v[208:211], v[216:219], v[114:117]
	v_mfma_f32_16x16x32_bf16 v[106:109], v[196:199], v[224:227], v[106:109]
	v_mfma_f32_16x16x32_bf16 v[98:101], v[208:211], v[224:227], v[98:101]
	v_mfma_f32_16x16x32_bf16 v[90:93], v[196:199], v[232:235], v[90:93]
	v_mfma_f32_16x16x32_bf16 v[82:85], v[208:211], v[232:235], v[82:85]
	v_mfma_f32_16x16x32_bf16 v[74:77], v[196:199], v[240:243], v[74:77]
	v_mfma_f32_16x16x32_bf16 v[66:69], v[208:211], v[240:243], v[66:69]
	s_barrier
	s_setprio 0
	s_add_i32 s29, s29, s84
	v_lshl_add_u64 v[172:173], v[244:245], 0, s[24:25]
	s_mov_b32 m0, s29
	ds_read_b128 v[212:215], v143 offset:49152
	ds_read_b128 v[216:219], v143 offset:50176
	ds_read_b128 v[220:223], v143 offset:51200
	ds_read_b128 v[224:227], v143 offset:52224
	ds_read_b128 v[228:231], v143 offset:53248
	ds_read_b128 v[232:235], v143 offset:54272
	ds_read_b128 v[236:239], v143 offset:55296
	ds_read_b128 v[240:243], v143 offset:56320
	global_load_lds_dwordx4 v[172:173], off
	s_add_i32 m0, s29, 0x2000
	s_add_u32 s42, s42, 0x40080
	v_lshl_add_u64 v[172:173], v[246:247], 0, s[24:25]
	s_addc_u32 s43, s43, 0
	s_add_i32 s29, s37, s84
	global_load_lds_dwordx4 v[172:173], off
	s_mov_b32 m0, s29
	v_lshl_add_u64 v[170:171], v[170:171], 0, s[24:25]
	global_load_lds_dwordx4 v138, s[42:43]
	s_add_i32 m0, s29, 0x2000
	s_nop 0
	global_load_lds_dwordx4 v134, s[42:43]
	v_lshl_add_u64 v[172:173], v[248:249], 0, s[24:25]
	s_mov_b32 m0, s97
	s_nop 0
	global_load_lds_dwordx4 v[172:173], off
	s_mov_b32 m0, s3
	s_nop 0
	global_load_lds_dwordx4 v[170:171], off
	s_waitcnt vmcnt(8)
	s_waitcnt lgkmcnt(0)
	s_setprio 1
	s_barrier
	v_mfma_f32_16x16x32_bf16 v[62:65], v[130:133], v[212:215], v[62:65]
	v_mfma_f32_16x16x32_bf16 v[54:57], v[184:187], v[212:215], v[54:57]
	v_mfma_f32_16x16x32_bf16 v[46:49], v[130:133], v[220:223], v[46:49]
	v_mfma_f32_16x16x32_bf16 v[38:41], v[184:187], v[220:223], v[38:41]
	v_mfma_f32_16x16x32_bf16 v[30:33], v[130:133], v[228:231], v[30:33]
	v_mfma_f32_16x16x32_bf16 v[22:25], v[184:187], v[228:231], v[22:25]
	v_mfma_f32_16x16x32_bf16 v[14:17], v[130:133], v[236:239], v[14:17]
	v_mfma_f32_16x16x32_bf16 v[6:9], v[184:187], v[236:239], v[6:9]
	v_mfma_f32_16x16x32_bf16 v[62:65], v[180:183], v[216:219], v[62:65]
	v_mfma_f32_16x16x32_bf16 v[54:57], v[188:191], v[216:219], v[54:57]
	v_mfma_f32_16x16x32_bf16 v[46:49], v[180:183], v[224:227], v[46:49]
	v_mfma_f32_16x16x32_bf16 v[38:41], v[188:191], v[224:227], v[38:41]
	v_mfma_f32_16x16x32_bf16 v[30:33], v[180:183], v[232:235], v[30:33]
	v_mfma_f32_16x16x32_bf16 v[22:25], v[188:191], v[232:235], v[22:25]
	v_mfma_f32_16x16x32_bf16 v[14:17], v[180:183], v[240:243], v[14:17]
	v_mfma_f32_16x16x32_bf16 v[6:9], v[188:191], v[240:243], v[6:9]
	v_mfma_f32_16x16x32_bf16 v[58:61], v[192:195], v[212:215], v[58:61]
	v_mfma_f32_16x16x32_bf16 v[50:53], v[204:207], v[212:215], v[50:53]
	v_mfma_f32_16x16x32_bf16 v[42:45], v[192:195], v[220:223], v[42:45]
	v_mfma_f32_16x16x32_bf16 v[34:37], v[204:207], v[220:223], v[34:37]
	v_mfma_f32_16x16x32_bf16 v[26:29], v[192:195], v[228:231], v[26:29]
	v_mfma_f32_16x16x32_bf16 v[18:21], v[204:207], v[228:231], v[18:21]
	v_mfma_f32_16x16x32_bf16 v[10:13], v[192:195], v[236:239], v[10:13]
	v_mfma_f32_16x16x32_bf16 v[2:5], v[204:207], v[236:239], v[2:5]
	v_mfma_f32_16x16x32_bf16 v[58:61], v[196:199], v[216:219], v[58:61]
	v_mfma_f32_16x16x32_bf16 v[50:53], v[208:211], v[216:219], v[50:53]
	v_mfma_f32_16x16x32_bf16 v[42:45], v[196:199], v[224:227], v[42:45]
	v_mfma_f32_16x16x32_bf16 v[34:37], v[208:211], v[224:227], v[34:37]
	v_mfma_f32_16x16x32_bf16 v[26:29], v[196:199], v[232:235], v[26:29]
	v_mfma_f32_16x16x32_bf16 v[18:21], v[208:211], v[232:235], v[18:21]
	v_mfma_f32_16x16x32_bf16 v[10:13], v[196:199], v[240:243], v[10:13]
	v_mfma_f32_16x16x32_bf16 v[2:5], v[208:211], v[240:243], v[2:5]
	s_barrier
	s_setprio 0
	s_add_u32 s16, s16, 0x100
	s_addc_u32 s17, s17, 0
	s_add_u32 s56, s56, 0x100
	s_addc_u32 s57, s57, 0
	s_cmp_ge_i32 s86, s23
	s_mov_b32 s42, s86
	s_cbranch_scc0 .LBB7_357
	s_branch .Lpeelx_357

.LBB7_521:
	s_add_u32 s52, s68, s18
	s_addc_u32 s53, s69, s19
	v_readlane_b32 s13, v254, 48
	s_add_u32 s54, s13, s50
	v_readlane_b32 s13, v254, 49
	s_addc_u32 s55, s13, s51
	s_andn2_b64 vcc, exec, s[8:9]
	s_cbranch_vccnz .LBB7_609
	s_and_b64 s[38:39], s[40:41], exec
	s_cselect_b32 s13, s53, s17
	s_cselect_b32 s15, s52, s16
	s_cselect_b32 s38, s55, s43
	s_cselect_b32 s39, s54, s42
	s_add_u32 s16, s16, 0x40080
	s_addc_u32 s17, s17, 0
	s_add_u32 s48, s42, 0x100
	s_addc_u32 s49, s43, 0
	s_mov_b32 s42, 0
.Lpeel_523:
	s_add_i32 s56, s42, 2
	s_add_u32 s29, s16, 0xfffc0080
	s_addc_u32 s37, s17, -1
	s_add_i32 s57, 0, 0x10000
	s_cmp_eq_u32 s84, s42
	s_cselect_b32 s45, s13, s37
	s_cselect_b32 s44, s15, s29
	v_add_u32_e32 v0, s57, v195
	s_cselect_b32 s43, s38, s49
	s_cselect_b32 s42, s39, s48
	s_add_i32 s29, 0, 0x14000
	ds_read_b128 v[130:133], v0
	ds_read_b128 v[150:153], v0 offset:1024
	ds_read_b128 v[154:157], v0 offset:2048
	ds_read_b128 v[158:161], v0 offset:3072
	v_add_u32_e32 v0, s29, v195
	ds_read_b128 v[174:177], v0
	ds_read_b128 v[178:181], v0 offset:1024
	ds_read_b128 v[182:185], v0 offset:2048
	ds_read_b128 v[186:189], v0 offset:3072
	s_add_i32 m0, s5, 0xc000
	ds_read_b128 v[190:193], v196
	ds_read_b128 v[204:207], v196 offset:1024
	ds_read_b128 v[208:211], v196 offset:2048
	ds_read_b128 v[212:215], v196 offset:3072
	ds_read_b128 v[216:219], v196 offset:4096
	ds_read_b128 v[220:223], v196 offset:5120
	ds_read_b128 v[224:227], v196 offset:6144
	ds_read_b128 v[228:231], v196 offset:7168
	global_load_lds_dwordx4 v146, s[16:17]
	s_add_i32 m0, s5, 0xe000
	s_nop 0
	global_load_lds_dwordx4 v148, s[16:17]
	s_waitcnt vmcnt(8)
	s_waitcnt lgkmcnt(0)
	s_setprio 1
	s_barrier
	v_mfma_f32_16x16x32_bf16 v[126:129], v[130:133], v[190:193], 0
	v_mfma_f32_16x16x32_bf16 v[122:125], v[154:157], v[190:193], 0
	v_mfma_f32_16x16x32_bf16 v[110:113], v[130:133], v[208:211], 0
	v_mfma_f32_16x16x32_bf16 v[106:109], v[154:157], v[208:211], 0
	v_mfma_f32_16x16x32_bf16 v[94:97], v[130:133], v[216:219], 0
	v_mfma_f32_16x16x32_bf16 v[90:93], v[154:157], v[216:219], 0
	v_mfma_f32_16x16x32_bf16 v[78:81], v[130:133], v[224:227], 0
	v_mfma_f32_16x16x32_bf16 v[74:77], v[154:157], v[224:227], 0
	v_mfma_f32_16x16x32_bf16 v[126:129], v[150:153], v[204:207], v[126:129]
	v_mfma_f32_16x16x32_bf16 v[122:125], v[158:161], v[204:207], v[122:125]
	v_mfma_f32_16x16x32_bf16 v[110:113], v[150:153], v[212:215], v[110:113]
	v_mfma_f32_16x16x32_bf16 v[106:109], v[158:161], v[212:215], v[106:109]
	v_mfma_f32_16x16x32_bf16 v[94:97], v[150:153], v[220:223], v[94:97]
	v_mfma_f32_16x16x32_bf16 v[90:93], v[158:161], v[220:223], v[90:93]
	v_mfma_f32_16x16x32_bf16 v[78:81], v[150:153], v[228:231], v[78:81]
	v_mfma_f32_16x16x32_bf16 v[74:77], v[158:161], v[228:231], v[74:77]
	v_mfma_f32_16x16x32_bf16 v[118:121], v[174:177], v[190:193], 0
	v_mfma_f32_16x16x32_bf16 v[114:117], v[182:185], v[190:193], 0
	v_mfma_f32_16x16x32_bf16 v[102:105], v[174:177], v[208:211], 0
	v_mfma_f32_16x16x32_bf16 v[98:101], v[182:185], v[208:211], 0
	v_mfma_f32_16x16x32_bf16 v[86:89], v[174:177], v[216:219], 0
	v_mfma_f32_16x16x32_bf16 v[82:85], v[182:185], v[216:219], 0
	v_mfma_f32_16x16x32_bf16 v[70:73], v[174:177], v[224:227], 0
	v_mfma_f32_16x16x32_bf16 v[66:69], v[182:185], v[224:227], 0
	v_mfma_f32_16x16x32_bf16 v[118:121], v[178:181], v[204:207], v[118:121]
	v_mfma_f32_16x16x32_bf16 v[114:117], v[186:189], v[204:207], v[114:117]
	v_mfma_f32_16x16x32_bf16 v[102:105], v[178:181], v[212:215], v[102:105]
	v_mfma_f32_16x16x32_bf16 v[98:101], v[186:189], v[212:215], v[98:101]
	v_mfma_f32_16x16x32_bf16 v[86:89], v[178:181], v[220:223], v[86:89]
	v_mfma_f32_16x16x32_bf16 v[82:85], v[186:189], v[220:223], v[82:85]
	v_mfma_f32_16x16x32_bf16 v[70:73], v[178:181], v[228:231], v[70:73]
	v_mfma_f32_16x16x32_bf16 v[66:69], v[186:189], v[228:231], v[66:69]
	s_barrier
	s_setprio 0
	s_add_i32 s37, s57, s4
	v_lshl_add_u64 v[170:171], s[42:43], 0, v[138:139]
	s_mov_b32 m0, s37
	ds_read_b128 v[190:193], v196 offset:16384
	ds_read_b128 v[204:207], v196 offset:17408
	ds_read_b128 v[208:211], v196 offset:18432
	ds_read_b128 v[212:215], v196 offset:19456
	ds_read_b128 v[216:219], v196 offset:20480
	ds_read_b128 v[220:223], v196 offset:21504
	ds_read_b128 v[224:227], v196 offset:22528
	ds_read_b128 v[228:231], v196 offset:23552
	global_load_lds_dwordx4 v[170:171], off
	s_add_i32 m0, s37, 0x2000
	s_add_u32 s74, s42, 0x40000
	v_lshl_add_u64 v[172:173], s[42:43], 0, v[134:135]
	s_addc_u32 s75, s43, 0
	s_add_i32 s29, s29, s4
	global_load_lds_dwordx4 v[172:173], off
	s_mov_b32 m0, s29
	v_lshl_add_u64 v[232:233], s[44:45], 0, v[136:137]
	global_load_lds_dwordx4 v138, s[74:75]
	s_add_i32 m0, s29, 0x2000
	s_nop 0
	global_load_lds_dwordx4 v134, s[74:75]
	v_lshl_add_u64 v[198:199], s[44:45], 0, v[140:141]
	s_mov_b32 m0, s5
	s_nop 0
	global_load_lds_dwordx4 v[198:199], off
	s_mov_b32 m0, s20
	s_nop 0
	global_load_lds_dwordx4 v[232:233], off
	s_waitcnt vmcnt(8)
	s_waitcnt lgkmcnt(0)
	s_setprio 1
	s_barrier
	v_mfma_f32_16x16x32_bf16 v[62:65], v[130:133], v[190:193], 0
	v_mfma_f32_16x16x32_bf16 v[58:61], v[154:157], v[190:193], 0
	v_mfma_f32_16x16x32_bf16 v[46:49], v[130:133], v[208:211], 0
	v_mfma_f32_16x16x32_bf16 v[42:45], v[154:157], v[208:211], 0
	v_mfma_f32_16x16x32_bf16 v[30:33], v[130:133], v[216:219], 0
	v_mfma_f32_16x16x32_bf16 v[26:29], v[154:157], v[216:219], 0
	v_mfma_f32_16x16x32_bf16 v[14:17], v[130:133], v[224:227], 0
	v_mfma_f32_16x16x32_bf16 v[10:13], v[154:157], v[224:227], 0
	v_mfma_f32_16x16x32_bf16 v[62:65], v[150:153], v[204:207], v[62:65]
	v_mfma_f32_16x16x32_bf16 v[58:61], v[158:161], v[204:207], v[58:61]
	v_mfma_f32_16x16x32_bf16 v[46:49], v[150:153], v[212:215], v[46:49]
	v_mfma_f32_16x16x32_bf16 v[42:45], v[158:161], v[212:215], v[42:45]
	v_mfma_f32_16x16x32_bf16 v[30:33], v[150:153], v[220:223], v[30:33]
	v_mfma_f32_16x16x32_bf16 v[26:29], v[158:161], v[220:223], v[26:29]
	v_mfma_f32_16x16x32_bf16 v[14:17], v[150:153], v[228:231], v[14:17]
	v_mfma_f32_16x16x32_bf16 v[10:13], v[158:161], v[228:231], v[10:13]
	v_mfma_f32_16x16x32_bf16 v[54:57], v[174:177], v[190:193], 0
	v_mfma_f32_16x16x32_bf16 v[50:53], v[182:185], v[190:193], 0
	v_mfma_f32_16x16x32_bf16 v[38:41], v[174:177], v[208:211], 0
	v_mfma_f32_16x16x32_bf16 v[34:37], v[182:185], v[208:211], 0
	v_mfma_f32_16x16x32_bf16 v[22:25], v[174:177], v[216:219], 0
	v_mfma_f32_16x16x32_bf16 v[18:21], v[182:185], v[216:219], 0
	v_mfma_f32_16x16x32_bf16 v[6:9], v[174:177], v[224:227], 0
	v_mfma_f32_16x16x32_bf16 v[2:5], v[182:185], v[224:227], 0
	v_mfma_f32_16x16x32_bf16 v[54:57], v[178:181], v[204:207], v[54:57]
	v_mfma_f32_16x16x32_bf16 v[50:53], v[186:189], v[204:207], v[50:53]
	v_mfma_f32_16x16x32_bf16 v[38:41], v[178:181], v[212:215], v[38:41]
	v_mfma_f32_16x16x32_bf16 v[34:37], v[186:189], v[212:215], v[34:37]
	v_mfma_f32_16x16x32_bf16 v[22:25], v[178:181], v[220:223], v[22:25]
	v_mfma_f32_16x16x32_bf16 v[18:21], v[186:189], v[220:223], v[18:21]
	v_mfma_f32_16x16x32_bf16 v[6:9], v[178:181], v[228:231], v[6:9]
	v_mfma_f32_16x16x32_bf16 v[2:5], v[186:189], v[228:231], v[2:5]
	s_barrier
	s_setprio 0
	s_add_i32 s29, 0, 0x18000
	v_add_u32_e32 v0, s29, v195
	s_add_i32 s37, 0, 0x1c000
	ds_read_b128 v[130:133], v0
	ds_read_b128 v[150:153], v0 offset:1024
	ds_read_b128 v[154:157], v0 offset:2048
	ds_read_b128 v[158:161], v0 offset:3072
	v_add_u32_e32 v0, s37, v195
	ds_read_b128 v[174:177], v0
	ds_read_b128 v[178:181], v0 offset:1024
	ds_read_b128 v[182:185], v0 offset:2048
	ds_read_b128 v[186:189], v0 offset:3072
	s_add_u32 s44, s44, 0x40000
	s_addc_u32 s45, s45, 0
	s_mov_b32 m0, s22
	ds_read_b128 v[190:193], v196 offset:32768
	ds_read_b128 v[204:207], v196 offset:33792
	ds_read_b128 v[208:211], v196 offset:34816
	ds_read_b128 v[212:215], v196 offset:35840
	ds_read_b128 v[216:219], v196 offset:36864
	ds_read_b128 v[220:223], v196 offset:37888
	ds_read_b128 v[224:227], v196 offset:38912
	ds_read_b128 v[228:231], v196 offset:39936
	global_load_lds_dwordx4 v140, s[44:45]
	s_mov_b32 m0, s23
	s_nop 0
	global_load_lds_dwordx4 v136, s[44:45]
	s_waitcnt vmcnt(8)
	s_waitcnt lgkmcnt(0)
	s_setprio 1
	s_barrier
	v_mfma_f32_16x16x32_bf16 v[126:129], v[130:133], v[190:193], v[126:129]
	v_mfma_f32_16x16x32_bf16 v[122:125], v[154:157], v[190:193], v[122:125]
	v_mfma_f32_16x16x32_bf16 v[110:113], v[130:133], v[208:211], v[110:113]
	v_mfma_f32_16x16x32_bf16 v[106:109], v[154:157], v[208:211], v[106:109]
	v_mfma_f32_16x16x32_bf16 v[94:97], v[130:133], v[216:219], v[94:97]
	v_mfma_f32_16x16x32_bf16 v[90:93], v[154:157], v[216:219], v[90:93]
	v_mfma_f32_16x16x32_bf16 v[78:81], v[130:133], v[224:227], v[78:81]
	v_mfma_f32_16x16x32_bf16 v[74:77], v[154:157], v[224:227], v[74:77]
	v_mfma_f32_16x16x32_bf16 v[126:129], v[150:153], v[204:207], v[126:129]
	v_mfma_f32_16x16x32_bf16 v[122:125], v[158:161], v[204:207], v[122:125]
	v_mfma_f32_16x16x32_bf16 v[110:113], v[150:153], v[212:215], v[110:113]
	v_mfma_f32_16x16x32_bf16 v[106:109], v[158:161], v[212:215], v[106:109]
	v_mfma_f32_16x16x32_bf16 v[94:97], v[150:153], v[220:223], v[94:97]
	v_mfma_f32_16x16x32_bf16 v[90:93], v[158:161], v[220:223], v[90:93]
	v_mfma_f32_16x16x32_bf16 v[78:81], v[150:153], v[228:231], v[78:81]
	v_mfma_f32_16x16x32_bf16 v[74:77], v[158:161], v[228:231], v[74:77]
	v_mfma_f32_16x16x32_bf16 v[118:121], v[174:177], v[190:193], v[118:121]
	v_mfma_f32_16x16x32_bf16 v[114:117], v[182:185], v[190:193], v[114:117]
	v_mfma_f32_16x16x32_bf16 v[102:105], v[174:177], v[208:211], v[102:105]
	v_mfma_f32_16x16x32_bf16 v[98:101], v[182:185], v[208:211], v[98:101]
	v_mfma_f32_16x16x32_bf16 v[86:89], v[174:177], v[216:219], v[86:89]
	v_mfma_f32_16x16x32_bf16 v[82:85], v[182:185], v[216:219], v[82:85]
	v_mfma_f32_16x16x32_bf16 v[70:73], v[174:177], v[224:227], v[70:73]
	v_mfma_f32_16x16x32_bf16 v[66:69], v[182:185], v[224:227], v[66:69]
	v_mfma_f32_16x16x32_bf16 v[118:121], v[178:181], v[204:207], v[118:121]
	v_mfma_f32_16x16x32_bf16 v[114:117], v[186:189], v[204:207], v[114:117]
	v_mfma_f32_16x16x32_bf16 v[102:105], v[178:181], v[212:215], v[102:105]
	v_mfma_f32_16x16x32_bf16 v[98:101], v[186:189], v[212:215], v[98:101]
	v_mfma_f32_16x16x32_bf16 v[86:89], v[178:181], v[220:223], v[86:89]
	v_mfma_f32_16x16x32_bf16 v[82:85], v[186:189], v[220:223], v[82:85]
	v_mfma_f32_16x16x32_bf16 v[70:73], v[178:181], v[228:231], v[70:73]
	v_mfma_f32_16x16x32_bf16 v[66:69], v[186:189], v[228:231], v[66:69]
	s_barrier
	s_setprio 0
	s_add_i32 s29, s29, s4
	v_lshl_add_u64 v[170:171], v[170:171], 0, s[24:25]
	s_mov_b32 m0, s29
	ds_read_b128 v[190:193], v196 offset:49152
	ds_read_b128 v[204:207], v196 offset:50176
	ds_read_b128 v[208:211], v196 offset:51200
	ds_read_b128 v[212:215], v196 offset:52224
	ds_read_b128 v[216:219], v196 offset:53248
	ds_read_b128 v[220:223], v196 offset:54272
	ds_read_b128 v[224:227], v196 offset:55296
	ds_read_b128 v[228:231], v196 offset:56320
	global_load_lds_dwordx4 v[170:171], off
	s_add_i32 m0, s29, 0x2000
	s_add_u32 s42, s42, 0x40080
	v_lshl_add_u64 v[170:171], v[172:173], 0, s[24:25]
	s_addc_u32 s43, s43, 0
	s_add_i32 s29, s37, s4
	global_load_lds_dwordx4 v[170:171], off
	s_mov_b32 m0, s29
	s_nop 0
	global_load_lds_dwordx4 v138, s[42:43]
	s_add_i32 m0, s29, 0x2000
	s_nop 0
	global_load_lds_dwordx4 v134, s[42:43]
	v_lshl_add_u64 v[170:171], v[198:199], 0, s[24:25]
	s_mov_b32 m0, s33
	s_nop 0
	global_load_lds_dwordx4 v[170:171], off
	v_lshl_add_u64 v[170:171], v[232:233], 0, s[24:25]
	s_mov_b32 m0, s72
	s_nop 0
	global_load_lds_dwordx4 v[170:171], off
	s_waitcnt vmcnt(8)
	s_waitcnt lgkmcnt(0)
	s_setprio 1
	s_barrier
	v_mfma_f32_16x16x32_bf16 v[62:65], v[130:133], v[190:193], v[62:65]
	v_mfma_f32_16x16x32_bf16 v[58:61], v[154:157], v[190:193], v[58:61]
	v_mfma_f32_16x16x32_bf16 v[46:49], v[130:133], v[208:211], v[46:49]
	v_mfma_f32_16x16x32_bf16 v[42:45], v[154:157], v[208:211], v[42:45]
	v_mfma_f32_16x16x32_bf16 v[30:33], v[130:133], v[216:219], v[30:33]
	v_mfma_f32_16x16x32_bf16 v[26:29], v[154:157], v[216:219], v[26:29]
	v_mfma_f32_16x16x32_bf16 v[14:17], v[130:133], v[224:227], v[14:17]
	v_mfma_f32_16x16x32_bf16 v[10:13], v[154:157], v[224:227], v[10:13]
	v_mfma_f32_16x16x32_bf16 v[62:65], v[150:153], v[204:207], v[62:65]
	v_mfma_f32_16x16x32_bf16 v[58:61], v[158:161], v[204:207], v[58:61]
	v_mfma_f32_16x16x32_bf16 v[46:49], v[150:153], v[212:215], v[46:49]
	v_mfma_f32_16x16x32_bf16 v[42:45], v[158:161], v[212:215], v[42:45]
	v_mfma_f32_16x16x32_bf16 v[30:33], v[150:153], v[220:223], v[30:33]
	v_mfma_f32_16x16x32_bf16 v[26:29], v[158:161], v[220:223], v[26:29]
	v_mfma_f32_16x16x32_bf16 v[14:17], v[150:153], v[228:231], v[14:17]
	v_mfma_f32_16x16x32_bf16 v[10:13], v[158:161], v[228:231], v[10:13]
	v_mfma_f32_16x16x32_bf16 v[54:57], v[174:177], v[190:193], v[54:57]
	v_mfma_f32_16x16x32_bf16 v[50:53], v[182:185], v[190:193], v[50:53]
	v_mfma_f32_16x16x32_bf16 v[38:41], v[174:177], v[208:211], v[38:41]
	v_mfma_f32_16x16x32_bf16 v[34:37], v[182:185], v[208:211], v[34:37]
	v_mfma_f32_16x16x32_bf16 v[22:25], v[174:177], v[216:219], v[22:25]
	v_mfma_f32_16x16x32_bf16 v[18:21], v[182:185], v[216:219], v[18:21]
	v_mfma_f32_16x16x32_bf16 v[6:9], v[174:177], v[224:227], v[6:9]
	v_mfma_f32_16x16x32_bf16 v[2:5], v[182:185], v[224:227], v[2:5]
	v_mfma_f32_16x16x32_bf16 v[54:57], v[178:181], v[204:207], v[54:57]
	v_mfma_f32_16x16x32_bf16 v[50:53], v[186:189], v[204:207], v[50:53]
	v_mfma_f32_16x16x32_bf16 v[38:41], v[178:181], v[212:215], v[38:41]
	v_mfma_f32_16x16x32_bf16 v[34:37], v[186:189], v[212:215], v[34:37]
	v_mfma_f32_16x16x32_bf16 v[22:25], v[178:181], v[220:223], v[22:25]
	v_mfma_f32_16x16x32_bf16 v[18:21], v[186:189], v[220:223], v[18:21]
	v_mfma_f32_16x16x32_bf16 v[6:9], v[178:181], v[228:231], v[6:9]
	v_mfma_f32_16x16x32_bf16 v[2:5], v[186:189], v[228:231], v[2:5]
	s_barrier
	s_setprio 0
	s_add_u32 s16, s16, 0x100
	s_addc_u32 s17, s17, 0
	s_add_u32 s48, s48, 0x100
	s_addc_u32 s49, s49, 0
	s_cmp_ge_i32 s56, s3
	s_mov_b32 s42, s56
	s_cbranch_scc0 .LBB7_523
	s_branch .Lpeelx_523

.Lpeelx_523:
	s_mov_b32 s56, s61
	s_and_b64 vcc, exec, s[6:7]
	s_cbranch_vccz .LBB7_526

.LBB7_674:
	s_add_u32 s16, s70, s12
	s_addc_u32 s17, s71, s13
	v_readlane_b32 s18, v254, 24
	s_add_u32 s18, s18, s14
	v_readlane_b32 s19, v254, 25
	s_addc_u32 s19, s19, s15
	s_andn2_b64 vcc, exec, s[8:9]
	s_cbranch_vccnz .LBB7_682
	s_and_b64 s[48:49], s[40:41], exec
	s_cselect_b32 s56, s17, s43
	s_cselect_b32 s57, s16, s42
	s_cselect_b32 s72, s19, s45
	s_cselect_b32 s73, s18, s44
	s_add_u32 s84, s44, 0x100
	s_addc_u32 s85, s45, 0
	s_mov_b32 s37, 0
.Lpeel_676:
	s_add_i32 s29, s37, 2
	s_add_u32 s44, s42, 0x100
	s_addc_u32 s45, s43, 0
	s_add_i32 s74, 0, 0x10000
	v_add_u32_e32 v81, s74, v79
	ds_read_b128 v[82:85], v81
	ds_read_b128 v[86:89], v81 offset:1024
	ds_read_b128 v[90:93], v81 offset:2048
	ds_read_b128 v[94:97], v81 offset:3072
	s_cmp_eq_u32 s53, s37
	s_cselect_b32 s51, s56, s45
	s_cselect_b32 s50, s57, s44
	s_cselect_b32 s49, s72, s85
	s_cselect_b32 s48, s73, s84
	v_lshl_add_u64 v[130:131], s[42:43], 0, v[74:75]
	s_add_i32 m0, s5, 0xc000
	ds_read_b128 v[98:101], v80
	ds_read_b128 v[102:105], v80 offset:1024
	ds_read_b128 v[106:109], v80 offset:2048
	ds_read_b128 v[110:113], v80 offset:3072
	ds_read_b128 v[114:117], v80 offset:4096
	ds_read_b128 v[118:121], v80 offset:5120
	ds_read_b128 v[122:125], v80 offset:6144
	ds_read_b128 v[126:129], v80 offset:7168
	global_load_lds_dwordx4 v[130:131], off
	v_lshl_add_u64 v[130:131], s[42:43], 0, v[76:77]
	s_add_i32 m0, s5, 0xe000
	s_nop 0
	global_load_lds_dwordx4 v[130:131], off
	s_waitcnt vmcnt(8)
	s_waitcnt lgkmcnt(0)
	s_setprio 1
	s_barrier
	v_mfma_f32_16x16x32_bf16 v[62:65], v[82:85], v[98:101], 0
	v_mfma_f32_16x16x32_bf16 v[58:61], v[90:93], v[98:101], 0
	v_mfma_f32_16x16x32_bf16 v[54:57], v[82:85], v[106:109], 0
	v_mfma_f32_16x16x32_bf16 v[50:53], v[90:93], v[106:109], 0
	v_mfma_f32_16x16x32_bf16 v[46:49], v[82:85], v[114:117], 0
	v_mfma_f32_16x16x32_bf16 v[42:45], v[90:93], v[114:117], 0
	v_mfma_f32_16x16x32_bf16 v[38:41], v[82:85], v[122:125], 0
	v_mfma_f32_16x16x32_bf16 v[34:37], v[90:93], v[122:125], 0
	v_mfma_f32_16x16x32_bf16 v[62:65], v[86:89], v[102:105], v[62:65]
	v_mfma_f32_16x16x32_bf16 v[58:61], v[94:97], v[102:105], v[58:61]
	v_mfma_f32_16x16x32_bf16 v[54:57], v[86:89], v[110:113], v[54:57]
	v_mfma_f32_16x16x32_bf16 v[50:53], v[94:97], v[110:113], v[50:53]
	v_mfma_f32_16x16x32_bf16 v[46:49], v[86:89], v[118:121], v[46:49]
	v_mfma_f32_16x16x32_bf16 v[42:45], v[94:97], v[118:121], v[42:45]
	v_mfma_f32_16x16x32_bf16 v[38:41], v[86:89], v[126:129], v[38:41]
	v_mfma_f32_16x16x32_bf16 v[34:37], v[94:97], v[126:129], v[34:37]
	s_barrier
	s_setprio 0
	s_add_i32 s37, s74, s4
	v_lshl_add_u64 v[130:131], s[48:49], 0, v[70:71]
	s_mov_b32 m0, s37
	ds_read_b128 v[98:101], v80 offset:16384
	ds_read_b128 v[102:105], v80 offset:17408
	ds_read_b128 v[106:109], v80 offset:18432
	ds_read_b128 v[110:113], v80 offset:19456
	ds_read_b128 v[114:117], v80 offset:20480
	ds_read_b128 v[118:121], v80 offset:21504
	ds_read_b128 v[122:125], v80 offset:22528
	ds_read_b128 v[126:129], v80 offset:23552
	global_load_lds_dwordx4 v[130:131], off
	s_add_i32 m0, s37, 0x2000
	s_add_u32 s42, s48, 0x20000
	v_lshl_add_u64 v[132:133], s[48:49], 0, v[66:67]
	s_addc_u32 s43, s49, 0
	global_load_lds_dwordx4 v[132:133], off
	v_lshl_add_u64 v[134:135], s[42:43], 0, v[70:71]
	s_mov_b32 m0, s10
	v_lshl_add_u64 v[136:137], s[50:51], 0, v[68:69]
	global_load_lds_dwordx4 v[134:135], off
	v_lshl_add_u64 v[134:135], s[42:43], 0, v[66:67]
	s_mov_b32 m0, s20
	s_nop 0
	global_load_lds_dwordx4 v[134:135], off
	v_lshl_add_u64 v[134:135], s[50:51], 0, v[0:1]
	s_mov_b32 m0, s5
	s_nop 0
	global_load_lds_dwordx4 v[134:135], off
	s_mov_b32 m0, s22
	s_nop 0
	global_load_lds_dwordx4 v[136:137], off
	s_waitcnt vmcnt(8)
	s_waitcnt lgkmcnt(0)
	s_setprio 1
	s_barrier
	v_mfma_f32_16x16x32_bf16 v[30:33], v[82:85], v[98:101], 0
	v_mfma_f32_16x16x32_bf16 v[26:29], v[90:93], v[98:101], 0
	v_mfma_f32_16x16x32_bf16 v[22:25], v[82:85], v[106:109], 0
	v_mfma_f32_16x16x32_bf16 v[18:21], v[90:93], v[106:109], 0
	v_mfma_f32_16x16x32_bf16 v[14:17], v[82:85], v[114:117], 0
	v_mfma_f32_16x16x32_bf16 v[10:13], v[90:93], v[114:117], 0
	v_mfma_f32_16x16x32_bf16 v[6:9], v[82:85], v[122:125], 0
	v_mfma_f32_16x16x32_bf16 v[2:5], v[90:93], v[122:125], 0
	v_mfma_f32_16x16x32_bf16 v[30:33], v[86:89], v[102:105], v[30:33]
	v_mfma_f32_16x16x32_bf16 v[26:29], v[94:97], v[102:105], v[26:29]
	v_mfma_f32_16x16x32_bf16 v[22:25], v[86:89], v[110:113], v[22:25]
	v_mfma_f32_16x16x32_bf16 v[18:21], v[94:97], v[110:113], v[18:21]
	v_mfma_f32_16x16x32_bf16 v[14:17], v[86:89], v[118:121], v[14:17]
	v_mfma_f32_16x16x32_bf16 v[10:13], v[94:97], v[118:121], v[10:13]
	v_mfma_f32_16x16x32_bf16 v[6:9], v[86:89], v[126:129], v[6:9]
	v_mfma_f32_16x16x32_bf16 v[2:5], v[94:97], v[126:129], v[2:5]
	s_barrier
	s_setprio 0
	s_add_i32 s37, 0, 0x18000
	v_add_u32_e32 v81, s37, v79
	ds_read_b128 v[82:85], v81
	ds_read_b128 v[86:89], v81 offset:1024
	ds_read_b128 v[90:93], v81 offset:2048
	ds_read_b128 v[94:97], v81 offset:3072
	s_add_u32 s42, s50, 0x28000
	s_addc_u32 s43, s51, 0
	s_mov_b32 m0, s23
	v_lshl_add_u64 v[138:139], s[42:43], 0, v[0:1]
	ds_read_b128 v[98:101], v80 offset:32768
	ds_read_b128 v[102:105], v80 offset:33792
	ds_read_b128 v[106:109], v80 offset:34816
	ds_read_b128 v[110:113], v80 offset:35840
	ds_read_b128 v[114:117], v80 offset:36864
	ds_read_b128 v[118:121], v80 offset:37888
	ds_read_b128 v[122:125], v80 offset:38912
	ds_read_b128 v[126:129], v80 offset:39936
	global_load_lds_dwordx4 v[138:139], off
	v_lshl_add_u64 v[138:139], s[42:43], 0, v[68:69]
	s_mov_b32 m0, s28
	s_nop 0
	global_load_lds_dwordx4 v[138:139], off
	s_waitcnt vmcnt(8)
	s_waitcnt lgkmcnt(0)
	s_setprio 1
	s_barrier
	v_mfma_f32_16x16x32_bf16 v[62:65], v[82:85], v[98:101], v[62:65]
	v_mfma_f32_16x16x32_bf16 v[58:61], v[90:93], v[98:101], v[58:61]
	v_mfma_f32_16x16x32_bf16 v[54:57], v[82:85], v[106:109], v[54:57]
	v_mfma_f32_16x16x32_bf16 v[50:53], v[90:93], v[106:109], v[50:53]
	v_mfma_f32_16x16x32_bf16 v[46:49], v[82:85], v[114:117], v[46:49]
	v_mfma_f32_16x16x32_bf16 v[42:45], v[90:93], v[114:117], v[42:45]
	v_mfma_f32_16x16x32_bf16 v[38:41], v[82:85], v[122:125], v[38:41]
	v_mfma_f32_16x16x32_bf16 v[34:37], v[90:93], v[122:125], v[34:37]
	v_mfma_f32_16x16x32_bf16 v[62:65], v[86:89], v[102:105], v[62:65]
	v_mfma_f32_16x16x32_bf16 v[58:61], v[94:97], v[102:105], v[58:61]
	v_mfma_f32_16x16x32_bf16 v[54:57], v[86:89], v[110:113], v[54:57]
	v_mfma_f32_16x16x32_bf16 v[50:53], v[94:97], v[110:113], v[50:53]
	v_mfma_f32_16x16x32_bf16 v[46:49], v[86:89], v[118:121], v[46:49]
	v_mfma_f32_16x16x32_bf16 v[42:45], v[94:97], v[118:121], v[42:45]
	v_mfma_f32_16x16x32_bf16 v[38:41], v[86:89], v[126:129], v[38:41]
	v_mfma_f32_16x16x32_bf16 v[34:37], v[94:97], v[126:129], v[34:37]
	s_barrier
	s_setprio 0
	s_add_i32 s37, s37, s4
	v_lshl_add_u64 v[130:131], v[130:131], 0, s[24:25]
	s_mov_b32 m0, s37
	ds_read_b128 v[98:101], v80 offset:49152
	ds_read_b128 v[102:105], v80 offset:50176
	ds_read_b128 v[106:109], v80 offset:51200
	ds_read_b128 v[110:113], v80 offset:52224
	ds_read_b128 v[114:117], v80 offset:53248
	ds_read_b128 v[118:121], v80 offset:54272
	ds_read_b128 v[122:125], v80 offset:55296
	ds_read_b128 v[126:129], v80 offset:56320
	global_load_lds_dwordx4 v[130:131], off
	s_add_i32 m0, s37, 0x2000
	s_add_u32 s42, s48, 0x20080
	v_lshl_add_u64 v[130:131], v[132:133], 0, s[24:25]
	s_addc_u32 s43, s49, 0
	global_load_lds_dwordx4 v[130:131], off
	v_lshl_add_u64 v[130:131], s[42:43], 0, v[70:71]
	s_mov_b32 m0, s38
	s_nop 0
	global_load_lds_dwordx4 v[130:131], off
	v_lshl_add_u64 v[130:131], s[42:43], 0, v[66:67]
	s_mov_b32 m0, s39
	s_nop 0
	global_load_lds_dwordx4 v[130:131], off
	v_lshl_add_u64 v[130:131], v[134:135], 0, s[24:25]
	s_mov_b32 m0, s31
	s_nop 0
	global_load_lds_dwordx4 v[130:131], off
	v_lshl_add_u64 v[130:131], v[136:137], 0, s[24:25]
	s_mov_b32 m0, s33
	s_nop 0
	global_load_lds_dwordx4 v[130:131], off
	s_waitcnt vmcnt(8)
	s_waitcnt lgkmcnt(0)
	s_setprio 1
	s_barrier
	v_mfma_f32_16x16x32_bf16 v[30:33], v[82:85], v[98:101], v[30:33]
	v_mfma_f32_16x16x32_bf16 v[26:29], v[90:93], v[98:101], v[26:29]
	v_mfma_f32_16x16x32_bf16 v[22:25], v[82:85], v[106:109], v[22:25]
	v_mfma_f32_16x16x32_bf16 v[18:21], v[90:93], v[106:109], v[18:21]
	v_mfma_f32_16x16x32_bf16 v[14:17], v[82:85], v[114:117], v[14:17]
	v_mfma_f32_16x16x32_bf16 v[10:13], v[90:93], v[114:117], v[10:13]
	v_mfma_f32_16x16x32_bf16 v[6:9], v[82:85], v[122:125], v[6:9]
	v_mfma_f32_16x16x32_bf16 v[2:5], v[90:93], v[122:125], v[2:5]
	v_mfma_f32_16x16x32_bf16 v[30:33], v[86:89], v[102:105], v[30:33]
	v_mfma_f32_16x16x32_bf16 v[26:29], v[94:97], v[102:105], v[26:29]
	v_mfma_f32_16x16x32_bf16 v[22:25], v[86:89], v[110:113], v[22:25]
	v_mfma_f32_16x16x32_bf16 v[18:21], v[94:97], v[110:113], v[18:21]
	v_mfma_f32_16x16x32_bf16 v[14:17], v[86:89], v[118:121], v[14:17]
	v_mfma_f32_16x16x32_bf16 v[10:13], v[94:97], v[118:121], v[10:13]
	v_mfma_f32_16x16x32_bf16 v[6:9], v[86:89], v[126:129], v[6:9]
	v_mfma_f32_16x16x32_bf16 v[2:5], v[94:97], v[126:129], v[2:5]
	s_barrier
	s_setprio 0
	s_add_u32 s84, s84, 0x100
	s_addc_u32 s85, s85, 0
	s_cmp_ge_i32 s29, s3
	s_mov_b64 s[42:43], s[44:45]
	s_mov_b32 s37, s29
	s_cbranch_scc0 .LBB7_676
	s_branch .Lpeelx_676

.LBB7_884:
	s_cmp_eq_u32 s29, 0
	s_cselect_b32 s38, s3, s29
	s_add_u32 s14, s70, s8
	s_addc_u32 s15, s71, s9
	v_readlane_b32 s18, v252, 38
	s_add_u32 s18, s18, s12
	v_readlane_b32 s19, v252, 40
	s_addc_u32 s19, s19, s13
	s_cmp_lt_i32 s38, 1
	s_cbranch_scc1 .LBB7_892
	s_and_b64 s[44:45], s[40:41], exec
	s_cselect_b32 s39, s15, s17
	s_cselect_b32 s54, s14, s16
	s_cselect_b32 s55, s19, s43
	s_cselect_b32 s56, s18, s42
	s_add_i32 s57, s38, -2
	s_add_u32 s72, s42, 0x100
	s_addc_u32 s73, s43, 0
	s_mov_b32 s44, 0
.Lpeel_886:
	s_add_i32 s37, s44, 2
	s_add_u32 s42, s16, 0x100
	s_addc_u32 s43, s17, 0
	s_add_i32 s29, 0, 0x10000
	s_cmp_eq_u32 s57, s44
	s_cselect_b32 s49, s39, s43
	s_cselect_b32 s48, s54, s42
	s_cselect_b32 s45, s55, s73
	s_cselect_b32 s44, s56, s72
	s_add_i32 s74, 0, 0x14000
	v_add_u32_e32 v142, s29, v193
	v_add_u32_e32 v158, s74, v193
	ds_read_b128 v[74:77], v142
	ds_read_b128 v[78:81], v142 offset:1024
	ds_read_b128 v[138:141], v142 offset:2048
	ds_read_b128 v[142:145], v142 offset:3072
	ds_read_b128 v[146:149], v158
	ds_read_b128 v[150:153], v158 offset:1024
	ds_read_b128 v[154:157], v158 offset:2048
	ds_read_b128 v[158:161], v158 offset:3072
	v_lshl_add_u64 v[170:171], s[16:17], 0, v[184:185]
	s_add_i32 m0, s5, 0xc000
	ds_read_b128 v[188:191], v195
	ds_read_b128 v[196:199], v195 offset:1024
	ds_read_b128 v[204:207], v195 offset:2048
	ds_read_b128 v[208:211], v195 offset:3072
	ds_read_b128 v[212:215], v195 offset:4096
	ds_read_b128 v[216:219], v195 offset:5120
	ds_read_b128 v[220:223], v195 offset:6144
	ds_read_b128 v[224:227], v195 offset:7168
	global_load_lds_dwordx4 v[170:171], off
	v_lshl_add_u64 v[170:171], s[16:17], 0, v[186:187]
	s_add_i32 m0, s5, 0xe000
	s_nop 0
	global_load_lds_dwordx4 v[170:171], off
	s_waitcnt vmcnt(8)
	s_waitcnt lgkmcnt(0)
	s_setprio 1
	s_barrier
	v_mfma_f32_16x16x32_bf16 v[134:137], v[74:77], v[188:191], 0
	v_mfma_f32_16x16x32_bf16 v[130:133], v[138:141], v[188:191], 0
	v_mfma_f32_16x16x32_bf16 v[118:121], v[74:77], v[204:207], 0
	v_mfma_f32_16x16x32_bf16 v[114:117], v[138:141], v[204:207], 0
	v_mfma_f32_16x16x32_bf16 v[102:105], v[74:77], v[212:215], 0
	v_mfma_f32_16x16x32_bf16 v[98:101], v[138:141], v[212:215], 0
	v_mfma_f32_16x16x32_bf16 v[86:89], v[74:77], v[220:223], 0
	v_mfma_f32_16x16x32_bf16 v[82:85], v[138:141], v[220:223], 0
	v_mfma_f32_16x16x32_bf16 v[134:137], v[78:81], v[196:199], v[134:137]
	v_mfma_f32_16x16x32_bf16 v[130:133], v[142:145], v[196:199], v[130:133]
	v_mfma_f32_16x16x32_bf16 v[118:121], v[78:81], v[208:211], v[118:121]
	v_mfma_f32_16x16x32_bf16 v[114:117], v[142:145], v[208:211], v[114:117]
	v_mfma_f32_16x16x32_bf16 v[102:105], v[78:81], v[216:219], v[102:105]
	v_mfma_f32_16x16x32_bf16 v[98:101], v[142:145], v[216:219], v[98:101]
	v_mfma_f32_16x16x32_bf16 v[86:89], v[78:81], v[224:227], v[86:89]
	v_mfma_f32_16x16x32_bf16 v[82:85], v[142:145], v[224:227], v[82:85]
	v_mfma_f32_16x16x32_bf16 v[126:129], v[146:149], v[188:191], 0
	v_mfma_f32_16x16x32_bf16 v[122:125], v[154:157], v[188:191], 0
	v_mfma_f32_16x16x32_bf16 v[110:113], v[146:149], v[204:207], 0
	v_mfma_f32_16x16x32_bf16 v[106:109], v[154:157], v[204:207], 0
	v_mfma_f32_16x16x32_bf16 v[94:97], v[146:149], v[212:215], 0
	v_mfma_f32_16x16x32_bf16 v[90:93], v[154:157], v[212:215], 0
	v_mfma_f32_16x16x32_bf16 v[70:73], v[146:149], v[220:223], 0
	v_mfma_f32_16x16x32_bf16 v[66:69], v[154:157], v[220:223], 0
	v_mfma_f32_16x16x32_bf16 v[126:129], v[150:153], v[196:199], v[126:129]
	v_mfma_f32_16x16x32_bf16 v[122:125], v[158:161], v[196:199], v[122:125]
	v_mfma_f32_16x16x32_bf16 v[110:113], v[150:153], v[208:211], v[110:113]
	v_mfma_f32_16x16x32_bf16 v[106:109], v[158:161], v[208:211], v[106:109]
	v_mfma_f32_16x16x32_bf16 v[94:97], v[150:153], v[216:219], v[94:97]
	v_mfma_f32_16x16x32_bf16 v[90:93], v[158:161], v[216:219], v[90:93]
	v_mfma_f32_16x16x32_bf16 v[70:73], v[150:153], v[224:227], v[70:73]
	v_mfma_f32_16x16x32_bf16 v[66:69], v[158:161], v[224:227], v[66:69]
	s_barrier
	s_setprio 0
	s_add_i32 s16, s29, s4
	v_lshl_add_u64 v[170:171], s[44:45], 0, v[178:179]
	s_mov_b32 m0, s16
	ds_read_b128 v[188:191], v195 offset:16384
	ds_read_b128 v[196:199], v195 offset:17408
	ds_read_b128 v[204:207], v195 offset:18432
	ds_read_b128 v[208:211], v195 offset:19456
	ds_read_b128 v[212:215], v195 offset:20480
	ds_read_b128 v[216:219], v195 offset:21504
	ds_read_b128 v[220:223], v195 offset:22528
	ds_read_b128 v[224:227], v195 offset:23552
	global_load_lds_dwordx4 v[170:171], off
	s_add_i32 m0, s16, 0x2000
	s_add_u32 s16, s44, 0x28000
	v_lshl_add_u64 v[172:173], s[44:45], 0, v[174:175]
	s_addc_u32 s17, s45, 0
	s_add_i32 s29, s74, s4
	global_load_lds_dwordx4 v[172:173], off
	v_lshl_add_u64 v[228:229], s[16:17], 0, v[178:179]
	s_mov_b32 m0, s29
	v_lshl_add_u64 v[230:231], s[48:49], 0, v[176:177]
	global_load_lds_dwordx4 v[228:229], off
	v_lshl_add_u64 v[228:229], s[16:17], 0, v[174:175]
	s_add_i32 m0, s29, 0x2000
	s_nop 0
	global_load_lds_dwordx4 v[228:229], off
	v_lshl_add_u64 v[228:229], s[48:49], 0, v[180:181]
	s_mov_b32 m0, s5
	s_nop 0
	global_load_lds_dwordx4 v[228:229], off
	s_mov_b32 m0, s20
	s_nop 0
	global_load_lds_dwordx4 v[230:231], off
	s_waitcnt vmcnt(8)
	s_waitcnt lgkmcnt(0)
	s_setprio 1
	s_barrier
	v_mfma_f32_16x16x32_bf16 v[62:65], v[74:77], v[188:191], 0
	v_mfma_f32_16x16x32_bf16 v[58:61], v[138:141], v[188:191], 0
	v_mfma_f32_16x16x32_bf16 v[46:49], v[74:77], v[204:207], 0
	v_mfma_f32_16x16x32_bf16 v[42:45], v[138:141], v[204:207], 0
	v_mfma_f32_16x16x32_bf16 v[30:33], v[74:77], v[212:215], 0
	v_mfma_f32_16x16x32_bf16 v[26:29], v[138:141], v[212:215], 0
	v_mfma_f32_16x16x32_bf16 v[14:17], v[74:77], v[220:223], 0
	v_mfma_f32_16x16x32_bf16 v[10:13], v[138:141], v[220:223], 0
	v_mfma_f32_16x16x32_bf16 v[62:65], v[78:81], v[196:199], v[62:65]
	v_mfma_f32_16x16x32_bf16 v[58:61], v[142:145], v[196:199], v[58:61]
	v_mfma_f32_16x16x32_bf16 v[46:49], v[78:81], v[208:211], v[46:49]
	v_mfma_f32_16x16x32_bf16 v[42:45], v[142:145], v[208:211], v[42:45]
	v_mfma_f32_16x16x32_bf16 v[30:33], v[78:81], v[216:219], v[30:33]
	v_mfma_f32_16x16x32_bf16 v[26:29], v[142:145], v[216:219], v[26:29]
	v_mfma_f32_16x16x32_bf16 v[14:17], v[78:81], v[224:227], v[14:17]
	v_mfma_f32_16x16x32_bf16 v[10:13], v[142:145], v[224:227], v[10:13]
	v_mfma_f32_16x16x32_bf16 v[54:57], v[146:149], v[188:191], 0
	v_mfma_f32_16x16x32_bf16 v[50:53], v[154:157], v[188:191], 0
	v_mfma_f32_16x16x32_bf16 v[38:41], v[146:149], v[204:207], 0
	v_mfma_f32_16x16x32_bf16 v[34:37], v[154:157], v[204:207], 0
	v_mfma_f32_16x16x32_bf16 v[22:25], v[146:149], v[212:215], 0
	v_mfma_f32_16x16x32_bf16 v[18:21], v[154:157], v[212:215], 0
	v_mfma_f32_16x16x32_bf16 v[6:9], v[146:149], v[220:223], 0
	v_mfma_f32_16x16x32_bf16 v[2:5], v[154:157], v[220:223], 0
	v_mfma_f32_16x16x32_bf16 v[54:57], v[150:153], v[196:199], v[54:57]
	v_mfma_f32_16x16x32_bf16 v[50:53], v[158:161], v[196:199], v[50:53]
	v_mfma_f32_16x16x32_bf16 v[38:41], v[150:153], v[208:211], v[38:41]
	v_mfma_f32_16x16x32_bf16 v[34:37], v[158:161], v[208:211], v[34:37]
	v_mfma_f32_16x16x32_bf16 v[22:25], v[150:153], v[216:219], v[22:25]
	v_mfma_f32_16x16x32_bf16 v[18:21], v[158:161], v[216:219], v[18:21]
	v_mfma_f32_16x16x32_bf16 v[6:9], v[150:153], v[224:227], v[6:9]
	v_mfma_f32_16x16x32_bf16 v[2:5], v[158:161], v[224:227], v[2:5]
	s_barrier
	s_setprio 0
	s_add_i32 s29, 0, 0x18000
	s_add_i32 s74, 0, 0x1c000
	v_add_u32_e32 v142, s29, v193
	v_add_u32_e32 v158, s74, v193
	ds_read_b128 v[74:77], v142
	ds_read_b128 v[78:81], v142 offset:1024
	ds_read_b128 v[138:141], v142 offset:2048
	ds_read_b128 v[142:145], v142 offset:3072
	ds_read_b128 v[146:149], v158
	ds_read_b128 v[150:153], v158 offset:1024
	ds_read_b128 v[154:157], v158 offset:2048
	ds_read_b128 v[158:161], v158 offset:3072
	s_add_u32 s16, s48, 0x28000
	s_addc_u32 s17, s49, 0
	s_mov_b32 m0, s22
	v_lshl_add_u64 v[232:233], s[16:17], 0, v[180:181]
	ds_read_b128 v[188:191], v195 offset:32768
	ds_read_b128 v[196:199], v195 offset:33792
	ds_read_b128 v[204:207], v195 offset:34816
	ds_read_b128 v[208:211], v195 offset:35840
	ds_read_b128 v[212:215], v195 offset:36864
	ds_read_b128 v[216:219], v195 offset:37888
	ds_read_b128 v[220:223], v195 offset:38912
	ds_read_b128 v[224:227], v195 offset:39936
	global_load_lds_dwordx4 v[232:233], off
	v_lshl_add_u64 v[232:233], s[16:17], 0, v[176:177]
	s_mov_b32 m0, s23
	s_nop 0
	global_load_lds_dwordx4 v[232:233], off
	s_waitcnt vmcnt(8)
	s_waitcnt lgkmcnt(0)
	s_setprio 1
	s_barrier
	v_mfma_f32_16x16x32_bf16 v[134:137], v[74:77], v[188:191], v[134:137]
	v_mfma_f32_16x16x32_bf16 v[130:133], v[138:141], v[188:191], v[130:133]
	v_mfma_f32_16x16x32_bf16 v[118:121], v[74:77], v[204:207], v[118:121]
	v_mfma_f32_16x16x32_bf16 v[114:117], v[138:141], v[204:207], v[114:117]
	v_mfma_f32_16x16x32_bf16 v[102:105], v[74:77], v[212:215], v[102:105]
	v_mfma_f32_16x16x32_bf16 v[98:101], v[138:141], v[212:215], v[98:101]
	v_mfma_f32_16x16x32_bf16 v[86:89], v[74:77], v[220:223], v[86:89]
	v_mfma_f32_16x16x32_bf16 v[82:85], v[138:141], v[220:223], v[82:85]
	v_mfma_f32_16x16x32_bf16 v[134:137], v[78:81], v[196:199], v[134:137]
	v_mfma_f32_16x16x32_bf16 v[130:133], v[142:145], v[196:199], v[130:133]
	v_mfma_f32_16x16x32_bf16 v[118:121], v[78:81], v[208:211], v[118:121]
	v_mfma_f32_16x16x32_bf16 v[114:117], v[142:145], v[208:211], v[114:117]
	v_mfma_f32_16x16x32_bf16 v[102:105], v[78:81], v[216:219], v[102:105]
	v_mfma_f32_16x16x32_bf16 v[98:101], v[142:145], v[216:219], v[98:101]
	v_mfma_f32_16x16x32_bf16 v[86:89], v[78:81], v[224:227], v[86:89]
	v_mfma_f32_16x16x32_bf16 v[82:85], v[142:145], v[224:227], v[82:85]
	v_mfma_f32_16x16x32_bf16 v[126:129], v[146:149], v[188:191], v[126:129]
	v_mfma_f32_16x16x32_bf16 v[122:125], v[154:157], v[188:191], v[122:125]
	v_mfma_f32_16x16x32_bf16 v[110:113], v[146:149], v[204:207], v[110:113]
	v_mfma_f32_16x16x32_bf16 v[106:109], v[154:157], v[204:207], v[106:109]
	v_mfma_f32_16x16x32_bf16 v[94:97], v[146:149], v[212:215], v[94:97]
	v_mfma_f32_16x16x32_bf16 v[90:93], v[154:157], v[212:215], v[90:93]
	v_mfma_f32_16x16x32_bf16 v[70:73], v[146:149], v[220:223], v[70:73]
	v_mfma_f32_16x16x32_bf16 v[66:69], v[154:157], v[220:223], v[66:69]
	v_mfma_f32_16x16x32_bf16 v[126:129], v[150:153], v[196:199], v[126:129]
	v_mfma_f32_16x16x32_bf16 v[122:125], v[158:161], v[196:199], v[122:125]
	v_mfma_f32_16x16x32_bf16 v[110:113], v[150:153], v[208:211], v[110:113]
	v_mfma_f32_16x16x32_bf16 v[106:109], v[158:161], v[208:211], v[106:109]
	v_mfma_f32_16x16x32_bf16 v[94:97], v[150:153], v[216:219], v[94:97]
	v_mfma_f32_16x16x32_bf16 v[90:93], v[158:161], v[216:219], v[90:93]
	v_mfma_f32_16x16x32_bf16 v[70:73], v[150:153], v[224:227], v[70:73]
	v_mfma_f32_16x16x32_bf16 v[66:69], v[158:161], v[224:227], v[66:69]
	s_barrier
	s_setprio 0
	s_add_i32 s16, s29, s4
	v_lshl_add_u64 v[170:171], v[170:171], 0, s[24:25]
	s_mov_b32 m0, s16
	ds_read_b128 v[188:191], v195 offset:49152
	ds_read_b128 v[196:199], v195 offset:50176
	ds_read_b128 v[204:207], v195 offset:51200
	ds_read_b128 v[208:211], v195 offset:52224
	ds_read_b128 v[212:215], v195 offset:53248
	ds_read_b128 v[216:219], v195 offset:54272
	ds_read_b128 v[220:223], v195 offset:55296
	ds_read_b128 v[224:227], v195 offset:56320
	global_load_lds_dwordx4 v[170:171], off
	s_add_i32 m0, s16, 0x2000
	s_add_u32 s16, s44, 0x28080
	v_lshl_add_u64 v[170:171], v[172:173], 0, s[24:25]
	s_addc_u32 s17, s45, 0
	s_add_i32 s29, s74, s4
	global_load_lds_dwordx4 v[170:171], off
	v_lshl_add_u64 v[170:171], s[16:17], 0, v[178:179]
	s_mov_b32 m0, s29
	s_nop 0
	global_load_lds_dwordx4 v[170:171], off
	v_lshl_add_u64 v[170:171], s[16:17], 0, v[174:175]
	s_add_i32 m0, s29, 0x2000
	s_nop 0
	global_load_lds_dwordx4 v[170:171], off
	v_lshl_add_u64 v[170:171], v[228:229], 0, s[24:25]
	s_mov_b32 m0, s31
	s_nop 0
	global_load_lds_dwordx4 v[170:171], off
	v_lshl_add_u64 v[170:171], v[230:231], 0, s[24:25]
	s_mov_b32 m0, s33
	s_nop 0
	global_load_lds_dwordx4 v[170:171], off
	s_waitcnt vmcnt(8)
	s_waitcnt lgkmcnt(0)
	s_setprio 1
	s_barrier
	v_mfma_f32_16x16x32_bf16 v[62:65], v[74:77], v[188:191], v[62:65]
	v_mfma_f32_16x16x32_bf16 v[58:61], v[138:141], v[188:191], v[58:61]
	v_mfma_f32_16x16x32_bf16 v[46:49], v[74:77], v[204:207], v[46:49]
	v_mfma_f32_16x16x32_bf16 v[42:45], v[138:141], v[204:207], v[42:45]
	v_mfma_f32_16x16x32_bf16 v[30:33], v[74:77], v[212:215], v[30:33]
	v_mfma_f32_16x16x32_bf16 v[26:29], v[138:141], v[212:215], v[26:29]
	v_mfma_f32_16x16x32_bf16 v[14:17], v[74:77], v[220:223], v[14:17]
	v_mfma_f32_16x16x32_bf16 v[10:13], v[138:141], v[220:223], v[10:13]
	v_mfma_f32_16x16x32_bf16 v[62:65], v[78:81], v[196:199], v[62:65]
	v_mfma_f32_16x16x32_bf16 v[58:61], v[142:145], v[196:199], v[58:61]
	v_mfma_f32_16x16x32_bf16 v[46:49], v[78:81], v[208:211], v[46:49]
	v_mfma_f32_16x16x32_bf16 v[42:45], v[142:145], v[208:211], v[42:45]
	v_mfma_f32_16x16x32_bf16 v[30:33], v[78:81], v[216:219], v[30:33]
	v_mfma_f32_16x16x32_bf16 v[26:29], v[142:145], v[216:219], v[26:29]
	v_mfma_f32_16x16x32_bf16 v[14:17], v[78:81], v[224:227], v[14:17]
	v_mfma_f32_16x16x32_bf16 v[10:13], v[142:145], v[224:227], v[10:13]
	v_mfma_f32_16x16x32_bf16 v[54:57], v[146:149], v[188:191], v[54:57]
	v_mfma_f32_16x16x32_bf16 v[50:53], v[154:157], v[188:191], v[50:53]
	v_mfma_f32_16x16x32_bf16 v[38:41], v[146:149], v[204:207], v[38:41]
	v_mfma_f32_16x16x32_bf16 v[34:37], v[154:157], v[204:207], v[34:37]
	v_mfma_f32_16x16x32_bf16 v[22:25], v[146:149], v[212:215], v[22:25]
	v_mfma_f32_16x16x32_bf16 v[18:21], v[154:157], v[212:215], v[18:21]
	v_mfma_f32_16x16x32_bf16 v[6:9], v[146:149], v[220:223], v[6:9]
	v_mfma_f32_16x16x32_bf16 v[2:5], v[154:157], v[220:223], v[2:5]
	v_mfma_f32_16x16x32_bf16 v[54:57], v[150:153], v[196:199], v[54:57]
	v_mfma_f32_16x16x32_bf16 v[50:53], v[158:161], v[196:199], v[50:53]
	v_mfma_f32_16x16x32_bf16 v[38:41], v[150:153], v[208:211], v[38:41]
	v_mfma_f32_16x16x32_bf16 v[34:37], v[158:161], v[208:211], v[34:37]
	v_mfma_f32_16x16x32_bf16 v[22:25], v[150:153], v[216:219], v[22:25]
	v_mfma_f32_16x16x32_bf16 v[18:21], v[158:161], v[216:219], v[18:21]
	v_mfma_f32_16x16x32_bf16 v[6:9], v[150:153], v[224:227], v[6:9]
	v_mfma_f32_16x16x32_bf16 v[2:5], v[158:161], v[224:227], v[2:5]
	s_barrier
	s_setprio 0
	s_add_u32 s72, s72, 0x100
	s_addc_u32 s73, s73, 0
	s_cmp_ge_i32 s37, s38
	s_mov_b64 s[16:17], s[42:43]
	s_mov_b32 s44, s37
	s_cbranch_scc0 .LBB7_886
	s_branch .Lpeelx_886

.LBB7_961:
	s_add_u32 s18, s46, s12
	s_addc_u32 s19, s47, s13
	v_readlane_b32 s29, v254, 56
	s_add_u32 s44, s29, s14
	v_readlane_b32 s29, v254, 57
	s_addc_u32 s45, s29, s15
	s_andn2_b64 vcc, exec, s[8:9]
	s_cbranch_vccnz .LBB7_1033
	s_and_b64 s[38:39], s[40:41], exec
	s_cselect_b32 s38, s19, s17
	s_cselect_b32 s39, s18, s16
	s_cselect_b32 s56, s45, s43
	s_cselect_b32 s57, s44, s42
	s_add_u32 s72, s42, 0x100
	s_addc_u32 s73, s43, 0
	s_mov_b32 s48, 0
	s_waitcnt vmcnt(0)
.Lpeel_963:
	s_add_i32 s37, s48, 2
	s_add_u32 s42, s16, 0x100
	s_addc_u32 s43, s17, 0
	s_add_i32 s29, 0, 0x10000
	s_cmp_eq_u32 s53, s48
	s_cselect_b32 s51, s38, s43
	s_cselect_b32 s50, s39, s42
	s_cselect_b32 s49, s56, s73
	s_cselect_b32 s48, s57, s72
	s_add_i32 s74, 0, 0x14000
	v_add_u32_e32 v142, s29, v197
	v_add_u32_e32 v158, s74, v197
	ds_read_b128 v[130:133], v142
	ds_read_b128 v[134:137], v142 offset:1024
	ds_read_b128 v[138:141], v142 offset:2048
	ds_read_b128 v[142:145], v142 offset:3072
	ds_read_b128 v[146:149], v158
	ds_read_b128 v[150:153], v158 offset:1024
	ds_read_b128 v[154:157], v158 offset:2048
	ds_read_b128 v[158:161], v158 offset:3072
	v_lshl_add_u64 v[170:171], s[16:17], 0, v[180:181]
	s_add_i32 m0, s5, 0xc000
	ds_read_b128 v[184:187], v199
	ds_read_b128 v[188:191], v199 offset:1024
	ds_read_b128 v[192:195], v199 offset:2048
	ds_read_b128 v[204:207], v199 offset:3072
	ds_read_b128 v[208:211], v199 offset:4096
	ds_read_b128 v[212:215], v199 offset:5120
	ds_read_b128 v[216:219], v199 offset:6144
	ds_read_b128 v[220:223], v199 offset:7168
	global_load_lds_dwordx4 v[170:171], off
	v_lshl_add_u64 v[170:171], s[16:17], 0, v[182:183]
	s_add_i32 m0, s5, 0xe000
	s_nop 0
	global_load_lds_dwordx4 v[170:171], off
	s_waitcnt vmcnt(8)
	s_waitcnt lgkmcnt(0)
	s_setprio 1
	s_barrier
	v_mfma_f32_16x16x32_bf16 v[126:129], v[130:133], v[184:187], 0
	v_mfma_f32_16x16x32_bf16 v[122:125], v[138:141], v[184:187], 0
	v_mfma_f32_16x16x32_bf16 v[110:113], v[130:133], v[192:195], 0
	v_mfma_f32_16x16x32_bf16 v[106:109], v[138:141], v[192:195], 0
	v_mfma_f32_16x16x32_bf16 v[94:97], v[130:133], v[208:211], 0
	v_mfma_f32_16x16x32_bf16 v[90:93], v[138:141], v[208:211], 0
	v_mfma_f32_16x16x32_bf16 v[78:81], v[130:133], v[216:219], 0
	v_mfma_f32_16x16x32_bf16 v[74:77], v[138:141], v[216:219], 0
	v_mfma_f32_16x16x32_bf16 v[126:129], v[134:137], v[188:191], v[126:129]
	v_mfma_f32_16x16x32_bf16 v[122:125], v[142:145], v[188:191], v[122:125]
	v_mfma_f32_16x16x32_bf16 v[110:113], v[134:137], v[204:207], v[110:113]
	v_mfma_f32_16x16x32_bf16 v[106:109], v[142:145], v[204:207], v[106:109]
	v_mfma_f32_16x16x32_bf16 v[94:97], v[134:137], v[212:215], v[94:97]
	v_mfma_f32_16x16x32_bf16 v[90:93], v[142:145], v[212:215], v[90:93]
	v_mfma_f32_16x16x32_bf16 v[78:81], v[134:137], v[220:223], v[78:81]
	v_mfma_f32_16x16x32_bf16 v[74:77], v[142:145], v[220:223], v[74:77]
	v_mfma_f32_16x16x32_bf16 v[118:121], v[146:149], v[184:187], 0
	v_mfma_f32_16x16x32_bf16 v[114:117], v[154:157], v[184:187], 0
	v_mfma_f32_16x16x32_bf16 v[102:105], v[146:149], v[192:195], 0
	v_mfma_f32_16x16x32_bf16 v[98:101], v[154:157], v[192:195], 0
	v_mfma_f32_16x16x32_bf16 v[86:89], v[146:149], v[208:211], 0
	v_mfma_f32_16x16x32_bf16 v[82:85], v[154:157], v[208:211], 0
	v_mfma_f32_16x16x32_bf16 v[70:73], v[146:149], v[216:219], 0
	v_mfma_f32_16x16x32_bf16 v[66:69], v[154:157], v[216:219], 0
	v_mfma_f32_16x16x32_bf16 v[118:121], v[150:153], v[188:191], v[118:121]
	v_mfma_f32_16x16x32_bf16 v[114:117], v[158:161], v[188:191], v[114:117]
	v_mfma_f32_16x16x32_bf16 v[102:105], v[150:153], v[204:207], v[102:105]
	v_mfma_f32_16x16x32_bf16 v[98:101], v[158:161], v[204:207], v[98:101]
	v_mfma_f32_16x16x32_bf16 v[86:89], v[150:153], v[212:215], v[86:89]
	v_mfma_f32_16x16x32_bf16 v[82:85], v[158:161], v[212:215], v[82:85]
	v_mfma_f32_16x16x32_bf16 v[70:73], v[150:153], v[220:223], v[70:73]
	v_mfma_f32_16x16x32_bf16 v[66:69], v[158:161], v[220:223], v[66:69]
	s_barrier
	s_setprio 0
	s_add_i32 s16, s29, s4
	v_lshl_add_u64 v[170:171], s[48:49], 0, v[0:1]
	s_mov_b32 m0, s16
	ds_read_b128 v[184:187], v199 offset:16384
	ds_read_b128 v[188:191], v199 offset:17408
	ds_read_b128 v[192:195], v199 offset:18432
	ds_read_b128 v[204:207], v199 offset:19456
	ds_read_b128 v[208:211], v199 offset:20480
	ds_read_b128 v[212:215], v199 offset:21504
	ds_read_b128 v[216:219], v199 offset:22528
	ds_read_b128 v[220:223], v199 offset:23552
	global_load_lds_dwordx4 v[170:171], off
	s_add_i32 m0, s16, 0x2000
	s_add_u32 s16, s48, 0x18000
	v_lshl_add_u64 v[172:173], s[48:49], 0, v[174:175]
	s_addc_u32 s17, s49, 0
	s_add_i32 s29, s74, s4
	global_load_lds_dwordx4 v[172:173], off
	v_lshl_add_u64 v[224:225], s[16:17], 0, v[0:1]
	s_mov_b32 m0, s29
	v_lshl_add_u64 v[226:227], s[50:51], 0, v[176:177]
	global_load_lds_dwordx4 v[224:225], off
	v_lshl_add_u64 v[224:225], s[16:17], 0, v[174:175]
	s_add_i32 m0, s29, 0x2000
	s_nop 0
	global_load_lds_dwordx4 v[224:225], off
	v_lshl_add_u64 v[224:225], s[50:51], 0, v[178:179]
	s_mov_b32 m0, s5
	s_nop 0
	global_load_lds_dwordx4 v[224:225], off
	s_mov_b32 m0, s20
	s_nop 0
	global_load_lds_dwordx4 v[226:227], off
	s_waitcnt vmcnt(8)
	s_waitcnt lgkmcnt(0)
	s_setprio 1
	s_barrier
	v_mfma_f32_16x16x32_bf16 v[62:65], v[130:133], v[184:187], 0
	v_mfma_f32_16x16x32_bf16 v[58:61], v[138:141], v[184:187], 0
	v_mfma_f32_16x16x32_bf16 v[46:49], v[130:133], v[192:195], 0
	v_mfma_f32_16x16x32_bf16 v[42:45], v[138:141], v[192:195], 0
	v_mfma_f32_16x16x32_bf16 v[30:33], v[130:133], v[208:211], 0
	v_mfma_f32_16x16x32_bf16 v[26:29], v[138:141], v[208:211], 0
	v_mfma_f32_16x16x32_bf16 v[14:17], v[130:133], v[216:219], 0
	v_mfma_f32_16x16x32_bf16 v[10:13], v[138:141], v[216:219], 0
	v_mfma_f32_16x16x32_bf16 v[62:65], v[134:137], v[188:191], v[62:65]
	v_mfma_f32_16x16x32_bf16 v[58:61], v[142:145], v[188:191], v[58:61]
	v_mfma_f32_16x16x32_bf16 v[46:49], v[134:137], v[204:207], v[46:49]
	v_mfma_f32_16x16x32_bf16 v[42:45], v[142:145], v[204:207], v[42:45]
	v_mfma_f32_16x16x32_bf16 v[30:33], v[134:137], v[212:215], v[30:33]
	v_mfma_f32_16x16x32_bf16 v[26:29], v[142:145], v[212:215], v[26:29]
	v_mfma_f32_16x16x32_bf16 v[14:17], v[134:137], v[220:223], v[14:17]
	v_mfma_f32_16x16x32_bf16 v[10:13], v[142:145], v[220:223], v[10:13]
	v_mfma_f32_16x16x32_bf16 v[54:57], v[146:149], v[184:187], 0
	v_mfma_f32_16x16x32_bf16 v[50:53], v[154:157], v[184:187], 0
	v_mfma_f32_16x16x32_bf16 v[38:41], v[146:149], v[192:195], 0
	v_mfma_f32_16x16x32_bf16 v[34:37], v[154:157], v[192:195], 0
	v_mfma_f32_16x16x32_bf16 v[22:25], v[146:149], v[208:211], 0
	v_mfma_f32_16x16x32_bf16 v[18:21], v[154:157], v[208:211], 0
	v_mfma_f32_16x16x32_bf16 v[6:9], v[146:149], v[216:219], 0
	v_mfma_f32_16x16x32_bf16 v[2:5], v[154:157], v[216:219], 0
	v_mfma_f32_16x16x32_bf16 v[54:57], v[150:153], v[188:191], v[54:57]
	v_mfma_f32_16x16x32_bf16 v[50:53], v[158:161], v[188:191], v[50:53]
	v_mfma_f32_16x16x32_bf16 v[38:41], v[150:153], v[204:207], v[38:41]
	v_mfma_f32_16x16x32_bf16 v[34:37], v[158:161], v[204:207], v[34:37]
	v_mfma_f32_16x16x32_bf16 v[22:25], v[150:153], v[212:215], v[22:25]
	v_mfma_f32_16x16x32_bf16 v[18:21], v[158:161], v[212:215], v[18:21]
	v_mfma_f32_16x16x32_bf16 v[6:9], v[150:153], v[220:223], v[6:9]
	v_mfma_f32_16x16x32_bf16 v[2:5], v[158:161], v[220:223], v[2:5]
	s_barrier
	s_setprio 0
	s_add_i32 s29, 0, 0x18000
	s_add_i32 s74, 0, 0x1c000
	v_add_u32_e32 v142, s29, v197
	v_add_u32_e32 v158, s74, v197
	ds_read_b128 v[130:133], v142
	ds_read_b128 v[134:137], v142 offset:1024
	ds_read_b128 v[138:141], v142 offset:2048
	ds_read_b128 v[142:145], v142 offset:3072
	ds_read_b128 v[146:149], v158
	ds_read_b128 v[150:153], v158 offset:1024
	ds_read_b128 v[154:157], v158 offset:2048
	ds_read_b128 v[158:161], v158 offset:3072
	s_add_u32 s16, s50, 0x18000
	s_addc_u32 s17, s51, 0
	s_mov_b32 m0, s22
	v_lshl_add_u64 v[228:229], s[16:17], 0, v[178:179]
	ds_read_b128 v[184:187], v199 offset:32768
	ds_read_b128 v[188:191], v199 offset:33792
	ds_read_b128 v[192:195], v199 offset:34816
	ds_read_b128 v[204:207], v199 offset:35840
	ds_read_b128 v[208:211], v199 offset:36864
	ds_read_b128 v[212:215], v199 offset:37888
	ds_read_b128 v[216:219], v199 offset:38912
	ds_read_b128 v[220:223], v199 offset:39936
	global_load_lds_dwordx4 v[228:229], off
	v_lshl_add_u64 v[228:229], s[16:17], 0, v[176:177]
	s_mov_b32 m0, s23
	s_nop 0
	global_load_lds_dwordx4 v[228:229], off
	s_waitcnt vmcnt(8)
	s_waitcnt lgkmcnt(0)
	s_setprio 1
	s_barrier
	v_mfma_f32_16x16x32_bf16 v[126:129], v[130:133], v[184:187], v[126:129]
	v_mfma_f32_16x16x32_bf16 v[122:125], v[138:141], v[184:187], v[122:125]
	v_mfma_f32_16x16x32_bf16 v[110:113], v[130:133], v[192:195], v[110:113]
	v_mfma_f32_16x16x32_bf16 v[106:109], v[138:141], v[192:195], v[106:109]
	v_mfma_f32_16x16x32_bf16 v[94:97], v[130:133], v[208:211], v[94:97]
	v_mfma_f32_16x16x32_bf16 v[90:93], v[138:141], v[208:211], v[90:93]
	v_mfma_f32_16x16x32_bf16 v[78:81], v[130:133], v[216:219], v[78:81]
	v_mfma_f32_16x16x32_bf16 v[74:77], v[138:141], v[216:219], v[74:77]
	v_mfma_f32_16x16x32_bf16 v[126:129], v[134:137], v[188:191], v[126:129]
	v_mfma_f32_16x16x32_bf16 v[122:125], v[142:145], v[188:191], v[122:125]
	v_mfma_f32_16x16x32_bf16 v[110:113], v[134:137], v[204:207], v[110:113]
	v_mfma_f32_16x16x32_bf16 v[106:109], v[142:145], v[204:207], v[106:109]
	v_mfma_f32_16x16x32_bf16 v[94:97], v[134:137], v[212:215], v[94:97]
	v_mfma_f32_16x16x32_bf16 v[90:93], v[142:145], v[212:215], v[90:93]
	v_mfma_f32_16x16x32_bf16 v[78:81], v[134:137], v[220:223], v[78:81]
	v_mfma_f32_16x16x32_bf16 v[74:77], v[142:145], v[220:223], v[74:77]
	v_mfma_f32_16x16x32_bf16 v[118:121], v[146:149], v[184:187], v[118:121]
	v_mfma_f32_16x16x32_bf16 v[114:117], v[154:157], v[184:187], v[114:117]
	v_mfma_f32_16x16x32_bf16 v[102:105], v[146:149], v[192:195], v[102:105]
	v_mfma_f32_16x16x32_bf16 v[98:101], v[154:157], v[192:195], v[98:101]
	v_mfma_f32_16x16x32_bf16 v[86:89], v[146:149], v[208:211], v[86:89]
	v_mfma_f32_16x16x32_bf16 v[82:85], v[154:157], v[208:211], v[82:85]
	v_mfma_f32_16x16x32_bf16 v[70:73], v[146:149], v[216:219], v[70:73]
	v_mfma_f32_16x16x32_bf16 v[66:69], v[154:157], v[216:219], v[66:69]
	v_mfma_f32_16x16x32_bf16 v[118:121], v[150:153], v[188:191], v[118:121]
	v_mfma_f32_16x16x32_bf16 v[114:117], v[158:161], v[188:191], v[114:117]
	v_mfma_f32_16x16x32_bf16 v[102:105], v[150:153], v[204:207], v[102:105]
	v_mfma_f32_16x16x32_bf16 v[98:101], v[158:161], v[204:207], v[98:101]
	v_mfma_f32_16x16x32_bf16 v[86:89], v[150:153], v[212:215], v[86:89]
	v_mfma_f32_16x16x32_bf16 v[82:85], v[158:161], v[212:215], v[82:85]
	v_mfma_f32_16x16x32_bf16 v[70:73], v[150:153], v[220:223], v[70:73]
	v_mfma_f32_16x16x32_bf16 v[66:69], v[158:161], v[220:223], v[66:69]
	s_barrier
	s_setprio 0
	s_add_i32 s16, s29, s4
	v_lshl_add_u64 v[170:171], v[170:171], 0, s[24:25]
	s_mov_b32 m0, s16
	ds_read_b128 v[184:187], v199 offset:49152
	ds_read_b128 v[188:191], v199 offset:50176
	ds_read_b128 v[192:195], v199 offset:51200
	ds_read_b128 v[204:207], v199 offset:52224
	ds_read_b128 v[208:211], v199 offset:53248
	ds_read_b128 v[212:215], v199 offset:54272
	ds_read_b128 v[216:219], v199 offset:55296
	ds_read_b128 v[220:223], v199 offset:56320
	global_load_lds_dwordx4 v[170:171], off
	s_add_i32 m0, s16, 0x2000
	s_add_u32 s16, s48, 0x18080
	v_lshl_add_u64 v[170:171], v[172:173], 0, s[24:25]
	s_addc_u32 s17, s49, 0
	s_add_i32 s29, s74, s4
	global_load_lds_dwordx4 v[170:171], off
	v_lshl_add_u64 v[170:171], s[16:17], 0, v[0:1]
	s_mov_b32 m0, s29
	s_nop 0
	global_load_lds_dwordx4 v[170:171], off
	v_lshl_add_u64 v[170:171], s[16:17], 0, v[174:175]
	s_add_i32 m0, s29, 0x2000
	s_nop 0
	global_load_lds_dwordx4 v[170:171], off
	v_lshl_add_u64 v[170:171], v[224:225], 0, s[24:25]
	s_mov_b32 m0, s31
	s_nop 0
	global_load_lds_dwordx4 v[170:171], off
	v_lshl_add_u64 v[170:171], v[226:227], 0, s[24:25]
	s_mov_b32 m0, s33
	s_nop 0
	global_load_lds_dwordx4 v[170:171], off
	s_waitcnt vmcnt(8)
	s_waitcnt lgkmcnt(0)
	s_setprio 1
	s_barrier
	v_mfma_f32_16x16x32_bf16 v[62:65], v[130:133], v[184:187], v[62:65]
	v_mfma_f32_16x16x32_bf16 v[58:61], v[138:141], v[184:187], v[58:61]
	v_mfma_f32_16x16x32_bf16 v[46:49], v[130:133], v[192:195], v[46:49]
	v_mfma_f32_16x16x32_bf16 v[42:45], v[138:141], v[192:195], v[42:45]
	v_mfma_f32_16x16x32_bf16 v[30:33], v[130:133], v[208:211], v[30:33]
	v_mfma_f32_16x16x32_bf16 v[26:29], v[138:141], v[208:211], v[26:29]
	v_mfma_f32_16x16x32_bf16 v[14:17], v[130:133], v[216:219], v[14:17]
	v_mfma_f32_16x16x32_bf16 v[10:13], v[138:141], v[216:219], v[10:13]
	v_mfma_f32_16x16x32_bf16 v[62:65], v[134:137], v[188:191], v[62:65]
	v_mfma_f32_16x16x32_bf16 v[58:61], v[142:145], v[188:191], v[58:61]
	v_mfma_f32_16x16x32_bf16 v[46:49], v[134:137], v[204:207], v[46:49]
	v_mfma_f32_16x16x32_bf16 v[42:45], v[142:145], v[204:207], v[42:45]
	v_mfma_f32_16x16x32_bf16 v[30:33], v[134:137], v[212:215], v[30:33]
	v_mfma_f32_16x16x32_bf16 v[26:29], v[142:145], v[212:215], v[26:29]
	v_mfma_f32_16x16x32_bf16 v[14:17], v[134:137], v[220:223], v[14:17]
	v_mfma_f32_16x16x32_bf16 v[10:13], v[142:145], v[220:223], v[10:13]
	v_mfma_f32_16x16x32_bf16 v[54:57], v[146:149], v[184:187], v[54:57]
	v_mfma_f32_16x16x32_bf16 v[50:53], v[154:157], v[184:187], v[50:53]
	v_mfma_f32_16x16x32_bf16 v[38:41], v[146:149], v[192:195], v[38:41]
	v_mfma_f32_16x16x32_bf16 v[34:37], v[154:157], v[192:195], v[34:37]
	v_mfma_f32_16x16x32_bf16 v[22:25], v[146:149], v[208:211], v[22:25]
	v_mfma_f32_16x16x32_bf16 v[18:21], v[154:157], v[208:211], v[18:21]
	v_mfma_f32_16x16x32_bf16 v[6:9], v[146:149], v[216:219], v[6:9]
	v_mfma_f32_16x16x32_bf16 v[2:5], v[154:157], v[216:219], v[2:5]
	v_mfma_f32_16x16x32_bf16 v[54:57], v[150:153], v[188:191], v[54:57]
	v_mfma_f32_16x16x32_bf16 v[50:53], v[158:161], v[188:191], v[50:53]
	v_mfma_f32_16x16x32_bf16 v[38:41], v[150:153], v[204:207], v[38:41]
	v_mfma_f32_16x16x32_bf16 v[34:37], v[158:161], v[204:207], v[34:37]
	v_mfma_f32_16x16x32_bf16 v[22:25], v[150:153], v[212:215], v[22:25]
	v_mfma_f32_16x16x32_bf16 v[18:21], v[158:161], v[212:215], v[18:21]
	v_mfma_f32_16x16x32_bf16 v[6:9], v[150:153], v[220:223], v[6:9]
	v_mfma_f32_16x16x32_bf16 v[2:5], v[158:161], v[220:223], v[2:5]
	s_barrier
	s_setprio 0
	s_add_u32 s72, s72, 0x100
	s_addc_u32 s73, s73, 0
	s_cmp_ge_i32 s37, s3
	s_mov_b64 s[16:17], s[42:43]
	s_mov_b32 s48, s37
	s_cbranch_scc0 .LBB7_963
	s_branch .Lpeelx_963

.LBB7_1194:
	s_add_u32 s48, s68, s18
	s_addc_u32 s49, s69, s19
	v_readlane_b32 s13, v254, 32
	s_add_u32 s50, s13, s44
	v_readlane_b32 s13, v254, 33
	s_addc_u32 s51, s13, s45
	s_andn2_b64 vcc, exec, s[8:9]
	s_cbranch_vccnz .LBB7_1202
	s_and_b64 s[28:29], s[40:41], exec
	s_cselect_b32 s13, s49, s17
	s_cselect_b32 s15, s48, s16
	s_cselect_b32 s28, s51, s43
	s_cselect_b32 s39, s50, s42
	s_add_u32 s16, s16, 0x40080
	s_addc_u32 s17, s17, 0
	s_add_u32 s56, s42, 0x100
	s_addc_u32 s57, s43, 0
	s_mov_b32 s42, 0
.Lpeel_1196:
	s_add_i32 s72, s42, 2
	s_add_u32 s29, s16, 0xfffc0080
	s_addc_u32 s37, s17, -1
	s_add_i32 s73, 0, 0x10000
	s_cmp_eq_u32 s55, s42
	s_cselect_b32 s53, s13, s37
	s_cselect_b32 s52, s15, s29
	v_add_u32_e32 v146, s73, v153
	s_cselect_b32 s43, s28, s57
	s_cselect_b32 s42, s39, s56
	s_add_i32 s29, 0, 0x14000
	ds_read_b128 v[130:133], v146
	ds_read_b128 v[156:159], v146 offset:1024
	ds_read_b128 v[174:177], v146 offset:2048
	ds_read_b128 v[178:181], v146 offset:3072
	v_add_u32_e32 v146, s29, v153
	ds_read_b128 v[182:185], v146
	ds_read_b128 v[186:189], v146 offset:1024
	ds_read_b128 v[190:193], v146 offset:2048
	ds_read_b128 v[194:197], v146 offset:3072
	s_add_i32 m0, s5, 0xc000
	ds_read_b128 v[204:207], v161
	ds_read_b128 v[208:211], v161 offset:1024
	ds_read_b128 v[212:215], v161 offset:2048
	ds_read_b128 v[216:219], v161 offset:3072
	ds_read_b128 v[220:223], v161 offset:4096
	ds_read_b128 v[224:227], v161 offset:5120
	ds_read_b128 v[228:231], v161 offset:6144
	ds_read_b128 v[232:235], v161 offset:7168
	global_load_lds_dwordx4 v142, s[16:17]
	s_add_i32 m0, s5, 0xe000
	s_nop 0
	global_load_lds_dwordx4 v144, s[16:17]
	s_waitcnt vmcnt(8)
	s_waitcnt lgkmcnt(0)
	s_setprio 1
	s_barrier
	v_mfma_f32_16x16x32_bf16 v[126:129], v[130:133], v[204:207], 0
	v_mfma_f32_16x16x32_bf16 v[122:125], v[174:177], v[204:207], 0
	v_mfma_f32_16x16x32_bf16 v[110:113], v[130:133], v[212:215], 0
	v_mfma_f32_16x16x32_bf16 v[106:109], v[174:177], v[212:215], 0
	v_mfma_f32_16x16x32_bf16 v[94:97], v[130:133], v[220:223], 0
	v_mfma_f32_16x16x32_bf16 v[90:93], v[174:177], v[220:223], 0
	v_mfma_f32_16x16x32_bf16 v[78:81], v[130:133], v[228:231], 0
	v_mfma_f32_16x16x32_bf16 v[74:77], v[174:177], v[228:231], 0
	v_mfma_f32_16x16x32_bf16 v[126:129], v[156:159], v[208:211], v[126:129]
	v_mfma_f32_16x16x32_bf16 v[122:125], v[178:181], v[208:211], v[122:125]
	v_mfma_f32_16x16x32_bf16 v[110:113], v[156:159], v[216:219], v[110:113]
	v_mfma_f32_16x16x32_bf16 v[106:109], v[178:181], v[216:219], v[106:109]
	v_mfma_f32_16x16x32_bf16 v[94:97], v[156:159], v[224:227], v[94:97]
	v_mfma_f32_16x16x32_bf16 v[90:93], v[178:181], v[224:227], v[90:93]
	v_mfma_f32_16x16x32_bf16 v[78:81], v[156:159], v[232:235], v[78:81]
	v_mfma_f32_16x16x32_bf16 v[74:77], v[178:181], v[232:235], v[74:77]
	v_mfma_f32_16x16x32_bf16 v[118:121], v[182:185], v[204:207], 0
	v_mfma_f32_16x16x32_bf16 v[114:117], v[190:193], v[204:207], 0
	v_mfma_f32_16x16x32_bf16 v[102:105], v[182:185], v[212:215], 0
	v_mfma_f32_16x16x32_bf16 v[98:101], v[190:193], v[212:215], 0
	v_mfma_f32_16x16x32_bf16 v[86:89], v[182:185], v[220:223], 0
	v_mfma_f32_16x16x32_bf16 v[82:85], v[190:193], v[220:223], 0
	v_mfma_f32_16x16x32_bf16 v[70:73], v[182:185], v[228:231], 0
	v_mfma_f32_16x16x32_bf16 v[66:69], v[190:193], v[228:231], 0
	v_mfma_f32_16x16x32_bf16 v[118:121], v[186:189], v[208:211], v[118:121]
	v_mfma_f32_16x16x32_bf16 v[114:117], v[194:197], v[208:211], v[114:117]
	v_mfma_f32_16x16x32_bf16 v[102:105], v[186:189], v[216:219], v[102:105]
	v_mfma_f32_16x16x32_bf16 v[98:101], v[194:197], v[216:219], v[98:101]
	v_mfma_f32_16x16x32_bf16 v[86:89], v[186:189], v[224:227], v[86:89]
	v_mfma_f32_16x16x32_bf16 v[82:85], v[194:197], v[224:227], v[82:85]
	v_mfma_f32_16x16x32_bf16 v[70:73], v[186:189], v[232:235], v[70:73]
	v_mfma_f32_16x16x32_bf16 v[66:69], v[194:197], v[232:235], v[66:69]
	s_barrier
	s_setprio 0
	s_add_i32 s37, s73, s4
	v_lshl_add_u64 v[146:147], s[42:43], 0, v[0:1]
	s_mov_b32 m0, s37
	ds_read_b128 v[204:207], v161 offset:16384
	ds_read_b128 v[208:211], v161 offset:17408
	ds_read_b128 v[212:215], v161 offset:18432
	ds_read_b128 v[216:219], v161 offset:19456
	ds_read_b128 v[220:223], v161 offset:20480
	ds_read_b128 v[224:227], v161 offset:21504
	ds_read_b128 v[228:231], v161 offset:22528
	ds_read_b128 v[232:235], v161 offset:23552
	global_load_lds_dwordx4 v[146:147], off
	s_add_i32 m0, s37, 0x2000
	s_add_u32 s74, s42, 0x40000
	v_lshl_add_u64 v[150:151], s[42:43], 0, v[134:135]
	s_addc_u32 s75, s43, 0
	s_add_i32 s29, s29, s4
	global_load_lds_dwordx4 v[150:151], off
	s_mov_b32 m0, s29
	v_lshl_add_u64 v[172:173], s[52:53], 0, v[136:137]
	global_load_lds_dwordx4 v0, s[74:75]
	s_add_i32 m0, s29, 0x2000
	s_nop 0
	global_load_lds_dwordx4 v134, s[74:75]
	v_lshl_add_u64 v[170:171], s[52:53], 0, v[138:139]
	s_mov_b32 m0, s5
	s_nop 0
	global_load_lds_dwordx4 v[170:171], off
	s_mov_b32 m0, s20
	s_nop 0
	global_load_lds_dwordx4 v[172:173], off
	s_waitcnt vmcnt(8)
	s_waitcnt lgkmcnt(0)
	s_setprio 1
	s_barrier
	v_mfma_f32_16x16x32_bf16 v[62:65], v[130:133], v[204:207], 0
	v_mfma_f32_16x16x32_bf16 v[58:61], v[174:177], v[204:207], 0
	v_mfma_f32_16x16x32_bf16 v[46:49], v[130:133], v[212:215], 0
	v_mfma_f32_16x16x32_bf16 v[42:45], v[174:177], v[212:215], 0
	v_mfma_f32_16x16x32_bf16 v[30:33], v[130:133], v[220:223], 0
	v_mfma_f32_16x16x32_bf16 v[26:29], v[174:177], v[220:223], 0
	v_mfma_f32_16x16x32_bf16 v[14:17], v[130:133], v[228:231], 0
	v_mfma_f32_16x16x32_bf16 v[10:13], v[174:177], v[228:231], 0
	v_mfma_f32_16x16x32_bf16 v[62:65], v[156:159], v[208:211], v[62:65]
	v_mfma_f32_16x16x32_bf16 v[58:61], v[178:181], v[208:211], v[58:61]
	v_mfma_f32_16x16x32_bf16 v[46:49], v[156:159], v[216:219], v[46:49]
	v_mfma_f32_16x16x32_bf16 v[42:45], v[178:181], v[216:219], v[42:45]
	v_mfma_f32_16x16x32_bf16 v[30:33], v[156:159], v[224:227], v[30:33]
	v_mfma_f32_16x16x32_bf16 v[26:29], v[178:181], v[224:227], v[26:29]
	v_mfma_f32_16x16x32_bf16 v[14:17], v[156:159], v[232:235], v[14:17]
	v_mfma_f32_16x16x32_bf16 v[10:13], v[178:181], v[232:235], v[10:13]
	v_mfma_f32_16x16x32_bf16 v[54:57], v[182:185], v[204:207], 0
	v_mfma_f32_16x16x32_bf16 v[50:53], v[190:193], v[204:207], 0
	v_mfma_f32_16x16x32_bf16 v[38:41], v[182:185], v[212:215], 0
	v_mfma_f32_16x16x32_bf16 v[34:37], v[190:193], v[212:215], 0
	v_mfma_f32_16x16x32_bf16 v[22:25], v[182:185], v[220:223], 0
	v_mfma_f32_16x16x32_bf16 v[18:21], v[190:193], v[220:223], 0
	v_mfma_f32_16x16x32_bf16 v[6:9], v[182:185], v[228:231], 0
	v_mfma_f32_16x16x32_bf16 v[2:5], v[190:193], v[228:231], 0
	v_mfma_f32_16x16x32_bf16 v[54:57], v[186:189], v[208:211], v[54:57]
	v_mfma_f32_16x16x32_bf16 v[50:53], v[194:197], v[208:211], v[50:53]
	v_mfma_f32_16x16x32_bf16 v[38:41], v[186:189], v[216:219], v[38:41]
	v_mfma_f32_16x16x32_bf16 v[34:37], v[194:197], v[216:219], v[34:37]
	v_mfma_f32_16x16x32_bf16 v[22:25], v[186:189], v[224:227], v[22:25]
	v_mfma_f32_16x16x32_bf16 v[18:21], v[194:197], v[224:227], v[18:21]
	v_mfma_f32_16x16x32_bf16 v[6:9], v[186:189], v[232:235], v[6:9]
	v_mfma_f32_16x16x32_bf16 v[2:5], v[194:197], v[232:235], v[2:5]
	s_barrier
	s_setprio 0
	s_add_i32 s29, 0, 0x18000
	v_add_u32_e32 v148, s29, v153
	s_add_i32 s37, 0, 0x1c000
	ds_read_b128 v[130:133], v148
	ds_read_b128 v[156:159], v148 offset:1024
	ds_read_b128 v[174:177], v148 offset:2048
	ds_read_b128 v[178:181], v148 offset:3072
	v_add_u32_e32 v148, s37, v153
	ds_read_b128 v[182:185], v148
	ds_read_b128 v[186:189], v148 offset:1024
	ds_read_b128 v[190:193], v148 offset:2048
	ds_read_b128 v[194:197], v148 offset:3072
	s_add_u32 s52, s52, 0x40000
	s_addc_u32 s53, s53, 0
	s_mov_b32 m0, s22
	ds_read_b128 v[204:207], v161 offset:32768
	ds_read_b128 v[208:211], v161 offset:33792
	ds_read_b128 v[212:215], v161 offset:34816
	ds_read_b128 v[216:219], v161 offset:35840
	ds_read_b128 v[220:223], v161 offset:36864
	ds_read_b128 v[224:227], v161 offset:37888
	ds_read_b128 v[228:231], v161 offset:38912
	ds_read_b128 v[232:235], v161 offset:39936
	global_load_lds_dwordx4 v138, s[52:53]
	s_mov_b32 m0, s23
	s_nop 0
	global_load_lds_dwordx4 v136, s[52:53]
	s_waitcnt vmcnt(8)
	s_waitcnt lgkmcnt(0)
	s_setprio 1
	s_barrier
	v_mfma_f32_16x16x32_bf16 v[126:129], v[130:133], v[204:207], v[126:129]
	v_mfma_f32_16x16x32_bf16 v[122:125], v[174:177], v[204:207], v[122:125]
	v_mfma_f32_16x16x32_bf16 v[110:113], v[130:133], v[212:215], v[110:113]
	v_mfma_f32_16x16x32_bf16 v[106:109], v[174:177], v[212:215], v[106:109]
	v_mfma_f32_16x16x32_bf16 v[94:97], v[130:133], v[220:223], v[94:97]
	v_mfma_f32_16x16x32_bf16 v[90:93], v[174:177], v[220:223], v[90:93]
	v_mfma_f32_16x16x32_bf16 v[78:81], v[130:133], v[228:231], v[78:81]
	v_mfma_f32_16x16x32_bf16 v[74:77], v[174:177], v[228:231], v[74:77]
	v_mfma_f32_16x16x32_bf16 v[126:129], v[156:159], v[208:211], v[126:129]
	v_mfma_f32_16x16x32_bf16 v[122:125], v[178:181], v[208:211], v[122:125]
	v_mfma_f32_16x16x32_bf16 v[110:113], v[156:159], v[216:219], v[110:113]
	v_mfma_f32_16x16x32_bf16 v[106:109], v[178:181], v[216:219], v[106:109]
	v_mfma_f32_16x16x32_bf16 v[94:97], v[156:159], v[224:227], v[94:97]
	v_mfma_f32_16x16x32_bf16 v[90:93], v[178:181], v[224:227], v[90:93]
	v_mfma_f32_16x16x32_bf16 v[78:81], v[156:159], v[232:235], v[78:81]
	v_mfma_f32_16x16x32_bf16 v[74:77], v[178:181], v[232:235], v[74:77]
	v_mfma_f32_16x16x32_bf16 v[118:121], v[182:185], v[204:207], v[118:121]
	v_mfma_f32_16x16x32_bf16 v[114:117], v[190:193], v[204:207], v[114:117]
	v_mfma_f32_16x16x32_bf16 v[102:105], v[182:185], v[212:215], v[102:105]
	v_mfma_f32_16x16x32_bf16 v[98:101], v[190:193], v[212:215], v[98:101]
	v_mfma_f32_16x16x32_bf16 v[86:89], v[182:185], v[220:223], v[86:89]
	v_mfma_f32_16x16x32_bf16 v[82:85], v[190:193], v[220:223], v[82:85]
	v_mfma_f32_16x16x32_bf16 v[70:73], v[182:185], v[228:231], v[70:73]
	v_mfma_f32_16x16x32_bf16 v[66:69], v[190:193], v[228:231], v[66:69]
	v_mfma_f32_16x16x32_bf16 v[118:121], v[186:189], v[208:211], v[118:121]
	v_mfma_f32_16x16x32_bf16 v[114:117], v[194:197], v[208:211], v[114:117]
	v_mfma_f32_16x16x32_bf16 v[102:105], v[186:189], v[216:219], v[102:105]
	v_mfma_f32_16x16x32_bf16 v[98:101], v[194:197], v[216:219], v[98:101]
	v_mfma_f32_16x16x32_bf16 v[86:89], v[186:189], v[224:227], v[86:89]
	v_mfma_f32_16x16x32_bf16 v[82:85], v[194:197], v[224:227], v[82:85]
	v_mfma_f32_16x16x32_bf16 v[70:73], v[186:189], v[232:235], v[70:73]
	v_mfma_f32_16x16x32_bf16 v[66:69], v[194:197], v[232:235], v[66:69]
	s_barrier
	s_setprio 0
	s_add_i32 s29, s29, s4
	v_lshl_add_u64 v[146:147], v[146:147], 0, s[24:25]
	s_mov_b32 m0, s29
	ds_read_b128 v[204:207], v161 offset:49152
	ds_read_b128 v[208:211], v161 offset:50176
	ds_read_b128 v[212:215], v161 offset:51200
	ds_read_b128 v[216:219], v161 offset:52224
	ds_read_b128 v[220:223], v161 offset:53248
	ds_read_b128 v[224:227], v161 offset:54272
	ds_read_b128 v[228:231], v161 offset:55296
	ds_read_b128 v[232:235], v161 offset:56320
	global_load_lds_dwordx4 v[146:147], off
	s_add_i32 m0, s29, 0x2000
	s_add_u32 s42, s42, 0x40080
	v_lshl_add_u64 v[146:147], v[150:151], 0, s[24:25]
	s_addc_u32 s43, s43, 0
	s_add_i32 s29, s37, s4
	global_load_lds_dwordx4 v[146:147], off
	s_mov_b32 m0, s29
	s_nop 0
	global_load_lds_dwordx4 v0, s[42:43]
	s_add_i32 m0, s29, 0x2000
	s_nop 0
	global_load_lds_dwordx4 v134, s[42:43]
	v_lshl_add_u64 v[146:147], v[170:171], 0, s[24:25]
	s_mov_b32 m0, s31
	s_nop 0
	global_load_lds_dwordx4 v[146:147], off
	v_lshl_add_u64 v[146:147], v[172:173], 0, s[24:25]
	s_mov_b32 m0, s33
	s_nop 0
	global_load_lds_dwordx4 v[146:147], off
	s_waitcnt vmcnt(8)
	s_waitcnt lgkmcnt(0)
	s_setprio 1
	s_barrier
	v_mfma_f32_16x16x32_bf16 v[62:65], v[130:133], v[204:207], v[62:65]
	v_mfma_f32_16x16x32_bf16 v[58:61], v[174:177], v[204:207], v[58:61]
	v_mfma_f32_16x16x32_bf16 v[46:49], v[130:133], v[212:215], v[46:49]
	v_mfma_f32_16x16x32_bf16 v[42:45], v[174:177], v[212:215], v[42:45]
	v_mfma_f32_16x16x32_bf16 v[30:33], v[130:133], v[220:223], v[30:33]
	v_mfma_f32_16x16x32_bf16 v[26:29], v[174:177], v[220:223], v[26:29]
	v_mfma_f32_16x16x32_bf16 v[14:17], v[130:133], v[228:231], v[14:17]
	v_mfma_f32_16x16x32_bf16 v[10:13], v[174:177], v[228:231], v[10:13]
	v_mfma_f32_16x16x32_bf16 v[62:65], v[156:159], v[208:211], v[62:65]
	v_mfma_f32_16x16x32_bf16 v[58:61], v[178:181], v[208:211], v[58:61]
	v_mfma_f32_16x16x32_bf16 v[46:49], v[156:159], v[216:219], v[46:49]
	v_mfma_f32_16x16x32_bf16 v[42:45], v[178:181], v[216:219], v[42:45]
	v_mfma_f32_16x16x32_bf16 v[30:33], v[156:159], v[224:227], v[30:33]
	v_mfma_f32_16x16x32_bf16 v[26:29], v[178:181], v[224:227], v[26:29]
	v_mfma_f32_16x16x32_bf16 v[14:17], v[156:159], v[232:235], v[14:17]
	v_mfma_f32_16x16x32_bf16 v[10:13], v[178:181], v[232:235], v[10:13]
	v_mfma_f32_16x16x32_bf16 v[54:57], v[182:185], v[204:207], v[54:57]
	v_mfma_f32_16x16x32_bf16 v[50:53], v[190:193], v[204:207], v[50:53]
	v_mfma_f32_16x16x32_bf16 v[38:41], v[182:185], v[212:215], v[38:41]
	v_mfma_f32_16x16x32_bf16 v[34:37], v[190:193], v[212:215], v[34:37]
	v_mfma_f32_16x16x32_bf16 v[22:25], v[182:185], v[220:223], v[22:25]
	v_mfma_f32_16x16x32_bf16 v[18:21], v[190:193], v[220:223], v[18:21]
	v_mfma_f32_16x16x32_bf16 v[6:9], v[182:185], v[228:231], v[6:9]
	v_mfma_f32_16x16x32_bf16 v[2:5], v[190:193], v[228:231], v[2:5]
	v_mfma_f32_16x16x32_bf16 v[54:57], v[186:189], v[208:211], v[54:57]
	v_mfma_f32_16x16x32_bf16 v[50:53], v[194:197], v[208:211], v[50:53]
	v_mfma_f32_16x16x32_bf16 v[38:41], v[186:189], v[216:219], v[38:41]
	v_mfma_f32_16x16x32_bf16 v[34:37], v[194:197], v[216:219], v[34:37]
	v_mfma_f32_16x16x32_bf16 v[22:25], v[186:189], v[224:227], v[22:25]
	v_mfma_f32_16x16x32_bf16 v[18:21], v[194:197], v[224:227], v[18:21]
	v_mfma_f32_16x16x32_bf16 v[6:9], v[186:189], v[232:235], v[6:9]
	v_mfma_f32_16x16x32_bf16 v[2:5], v[194:197], v[232:235], v[2:5]
	s_barrier
	s_setprio 0
	s_add_u32 s16, s16, 0x100
	s_addc_u32 s17, s17, 0
	s_add_u32 s56, s56, 0x100
	s_addc_u32 s57, s57, 0
	s_cmp_ge_i32 s72, s3
	s_mov_b32 s42, s72
	s_cbranch_scc0 .LBB7_1196
	s_branch .Lpeelx_1196

.LBB7_1217:
	s_add_u32 s48, s94, s18
	s_addc_u32 s49, s95, s19
	s_add_u32 s50, s77, s44
	v_readlane_b32 s10, v250, 9
	s_addc_u32 s51, s10, s45
	s_andn2_b64 vcc, exec, s[8:9]
	s_cbranch_vccnz .LBB7_1257
	s_and_b64 s[28:29], s[42:43], exec
	s_cselect_b32 s10, s49, s17
	s_cselect_b32 s13, s48, s16
	s_cselect_b32 s15, s51, s53
	s_cselect_b32 s28, s50, s52
	s_add_u32 s16, s16, 0x40080
	s_addc_u32 s17, s17, 0
	s_add_u32 s38, s52, 0x100
	s_addc_u32 s39, s53, 0
	s_mov_b32 s52, 0
.Lpeel_1219:
	s_add_i32 s56, s52, 2
	s_add_u32 s29, s16, 0xfffc0080
	s_addc_u32 s37, s17, -1
	s_add_i32 s57, 0, 0x10000
	s_cmp_eq_u32 s84, s52
	s_cselect_b32 s55, s10, s37
	s_cselect_b32 s54, s13, s29
	s_cselect_b32 s53, s15, s39
	s_cselect_b32 s52, s28, s38
	s_add_i32 s29, 0, 0x14000
	v_add_u32_e32 v152, s57, v157
	v_add_u32_e32 v170, s29, v157
	ds_read_b128 v[140:143], v152
	ds_read_b128 v[144:147], v152 offset:1024
	ds_read_b128 v[148:151], v152 offset:2048
	ds_read_b128 v[152:155], v152 offset:3072
	ds_read_b128 v[184:187], v170
	ds_read_b128 v[188:191], v170 offset:1024
	ds_read_b128 v[192:195], v170 offset:2048
	ds_read_b128 v[196:199], v170 offset:3072
	s_add_i32 m0, s5, 0xc000
	ds_read_b128 v[204:207], v181
	ds_read_b128 v[208:211], v181 offset:1024
	ds_read_b128 v[212:215], v181 offset:2048
	ds_read_b128 v[216:219], v181 offset:3072
	ds_read_b128 v[220:223], v181 offset:4096
	ds_read_b128 v[224:227], v181 offset:5120
	ds_read_b128 v[228:231], v181 offset:6144
	ds_read_b128 v[232:235], v181 offset:7168
	global_load_lds_dwordx4 v136, s[16:17]
	s_add_i32 m0, s5, 0xe000
	s_nop 0
	global_load_lds_dwordx4 v138, s[16:17]
	s_waitcnt vmcnt(8)
	s_waitcnt lgkmcnt(0)
	s_setprio 1
	s_barrier
	v_mfma_f32_16x16x32_bf16 v[126:129], v[140:143], v[204:207], 0
	v_mfma_f32_16x16x32_bf16 v[122:125], v[148:151], v[204:207], 0
	v_mfma_f32_16x16x32_bf16 v[118:121], v[140:143], v[212:215], 0
	v_mfma_f32_16x16x32_bf16 v[114:117], v[148:151], v[212:215], 0
	v_mfma_f32_16x16x32_bf16 v[106:109], v[140:143], v[220:223], 0
	v_mfma_f32_16x16x32_bf16 v[98:101], v[148:151], v[220:223], 0
	v_mfma_f32_16x16x32_bf16 v[90:93], v[140:143], v[228:231], 0
	v_mfma_f32_16x16x32_bf16 v[82:85], v[148:151], v[228:231], 0
	v_mfma_f32_16x16x32_bf16 v[126:129], v[144:147], v[208:211], v[126:129]
	v_mfma_f32_16x16x32_bf16 v[122:125], v[152:155], v[208:211], v[122:125]
	v_mfma_f32_16x16x32_bf16 v[118:121], v[144:147], v[216:219], v[118:121]
	v_mfma_f32_16x16x32_bf16 v[114:117], v[152:155], v[216:219], v[114:117]
	v_mfma_f32_16x16x32_bf16 v[106:109], v[144:147], v[224:227], v[106:109]
	v_mfma_f32_16x16x32_bf16 v[98:101], v[152:155], v[224:227], v[98:101]
	v_mfma_f32_16x16x32_bf16 v[90:93], v[144:147], v[232:235], v[90:93]
	v_mfma_f32_16x16x32_bf16 v[82:85], v[152:155], v[232:235], v[82:85]
	v_mfma_f32_16x16x32_bf16 v[110:113], v[184:187], v[204:207], 0
	v_mfma_f32_16x16x32_bf16 v[102:105], v[192:195], v[204:207], 0
	v_mfma_f32_16x16x32_bf16 v[94:97], v[184:187], v[212:215], 0
	v_mfma_f32_16x16x32_bf16 v[86:89], v[192:195], v[212:215], 0
	v_mfma_f32_16x16x32_bf16 v[78:81], v[184:187], v[220:223], 0
	v_mfma_f32_16x16x32_bf16 v[74:77], v[192:195], v[220:223], 0
	v_mfma_f32_16x16x32_bf16 v[70:73], v[184:187], v[228:231], 0
	v_mfma_f32_16x16x32_bf16 v[66:69], v[192:195], v[228:231], 0
	v_mfma_f32_16x16x32_bf16 v[110:113], v[188:191], v[208:211], v[110:113]
	v_mfma_f32_16x16x32_bf16 v[102:105], v[196:199], v[208:211], v[102:105]
	v_mfma_f32_16x16x32_bf16 v[94:97], v[188:191], v[216:219], v[94:97]
	v_mfma_f32_16x16x32_bf16 v[86:89], v[196:199], v[216:219], v[86:89]
	v_mfma_f32_16x16x32_bf16 v[78:81], v[188:191], v[224:227], v[78:81]
	v_mfma_f32_16x16x32_bf16 v[74:77], v[196:199], v[224:227], v[74:77]
	v_mfma_f32_16x16x32_bf16 v[70:73], v[188:191], v[232:235], v[70:73]
	v_mfma_f32_16x16x32_bf16 v[66:69], v[196:199], v[232:235], v[66:69]
	s_barrier
	s_setprio 0
	s_add_i32 s37, s57, s4
	v_lshl_add_u64 v[170:171], s[52:53], 0, v[0:1]
	s_mov_b32 m0, s37
	ds_read_b128 v[204:207], v181 offset:16384
	ds_read_b128 v[208:211], v181 offset:17408
	ds_read_b128 v[212:215], v181 offset:18432
	ds_read_b128 v[216:219], v181 offset:19456
	ds_read_b128 v[220:223], v181 offset:20480
	ds_read_b128 v[224:227], v181 offset:21504
	ds_read_b128 v[228:231], v181 offset:22528
	ds_read_b128 v[232:235], v181 offset:23552
	global_load_lds_dwordx4 v[170:171], off
	s_add_i32 m0, s37, 0x2000
	s_add_u32 s74, s52, 0x40000
	v_lshl_add_u64 v[172:173], s[52:53], 0, v[130:131]
	s_addc_u32 s75, s53, 0
	s_add_i32 s29, s29, s4
	global_load_lds_dwordx4 v[172:173], off
	s_mov_b32 m0, s29
	v_lshl_add_u64 v[238:239], s[54:55], 0, v[132:133]
	global_load_lds_dwordx4 v0, s[74:75]
	s_add_i32 m0, s29, 0x2000
	s_nop 0
	global_load_lds_dwordx4 v130, s[74:75]
	v_lshl_add_u64 v[236:237], s[54:55], 0, v[134:135]
	s_mov_b32 m0, s5
	s_nop 0
	global_load_lds_dwordx4 v[236:237], off
	s_mov_b32 m0, s20
	s_nop 0
	global_load_lds_dwordx4 v[238:239], off
	s_waitcnt vmcnt(8)
	s_waitcnt lgkmcnt(0)
	s_setprio 1
	s_barrier
	v_mfma_f32_16x16x32_bf16 v[62:65], v[140:143], v[204:207], 0
	v_mfma_f32_16x16x32_bf16 v[58:61], v[148:151], v[204:207], 0
	v_mfma_f32_16x16x32_bf16 v[54:57], v[140:143], v[212:215], 0
	v_mfma_f32_16x16x32_bf16 v[50:53], v[148:151], v[212:215], 0
	v_mfma_f32_16x16x32_bf16 v[42:45], v[140:143], v[220:223], 0
	v_mfma_f32_16x16x32_bf16 v[34:37], v[148:151], v[220:223], 0
	v_mfma_f32_16x16x32_bf16 v[26:29], v[140:143], v[228:231], 0
	v_mfma_f32_16x16x32_bf16 v[18:21], v[148:151], v[228:231], 0
	v_mfma_f32_16x16x32_bf16 v[62:65], v[144:147], v[208:211], v[62:65]
	v_mfma_f32_16x16x32_bf16 v[58:61], v[152:155], v[208:211], v[58:61]
	v_mfma_f32_16x16x32_bf16 v[54:57], v[144:147], v[216:219], v[54:57]
	v_mfma_f32_16x16x32_bf16 v[50:53], v[152:155], v[216:219], v[50:53]
	v_mfma_f32_16x16x32_bf16 v[42:45], v[144:147], v[224:227], v[42:45]
	v_mfma_f32_16x16x32_bf16 v[34:37], v[152:155], v[224:227], v[34:37]
	v_mfma_f32_16x16x32_bf16 v[26:29], v[144:147], v[232:235], v[26:29]
	v_mfma_f32_16x16x32_bf16 v[18:21], v[152:155], v[232:235], v[18:21]
	v_mfma_f32_16x16x32_bf16 v[46:49], v[184:187], v[204:207], 0
	v_mfma_f32_16x16x32_bf16 v[38:41], v[192:195], v[204:207], 0
	v_mfma_f32_16x16x32_bf16 v[30:33], v[184:187], v[212:215], 0
	v_mfma_f32_16x16x32_bf16 v[22:25], v[192:195], v[212:215], 0
	v_mfma_f32_16x16x32_bf16 v[14:17], v[184:187], v[220:223], 0
	v_mfma_f32_16x16x32_bf16 v[10:13], v[192:195], v[220:223], 0
	v_mfma_f32_16x16x32_bf16 v[6:9], v[184:187], v[228:231], 0
	v_mfma_f32_16x16x32_bf16 v[2:5], v[192:195], v[228:231], 0
	v_mfma_f32_16x16x32_bf16 v[46:49], v[188:191], v[208:211], v[46:49]
	v_mfma_f32_16x16x32_bf16 v[38:41], v[196:199], v[208:211], v[38:41]
	v_mfma_f32_16x16x32_bf16 v[30:33], v[188:191], v[216:219], v[30:33]
	v_mfma_f32_16x16x32_bf16 v[22:25], v[196:199], v[216:219], v[22:25]
	v_mfma_f32_16x16x32_bf16 v[14:17], v[188:191], v[224:227], v[14:17]
	v_mfma_f32_16x16x32_bf16 v[10:13], v[196:199], v[224:227], v[10:13]
	v_mfma_f32_16x16x32_bf16 v[6:9], v[188:191], v[232:235], v[6:9]
	v_mfma_f32_16x16x32_bf16 v[2:5], v[196:199], v[232:235], v[2:5]
	s_barrier
	s_setprio 0
	s_add_i32 s29, 0, 0x18000
	s_add_i32 s37, 0, 0x1c000
	v_add_u32_e32 v152, s29, v157
	v_add_u32_e32 v183, s37, v157
	ds_read_b128 v[140:143], v152
	ds_read_b128 v[144:147], v152 offset:1024
	ds_read_b128 v[148:151], v152 offset:2048
	ds_read_b128 v[152:155], v152 offset:3072
	ds_read_b128 v[184:187], v183
	ds_read_b128 v[188:191], v183 offset:1024
	ds_read_b128 v[192:195], v183 offset:2048
	ds_read_b128 v[196:199], v183 offset:3072
	s_add_u32 s54, s54, 0x40000
	s_addc_u32 s55, s55, 0
	s_mov_b32 m0, s22
	ds_read_b128 v[204:207], v181 offset:32768
	ds_read_b128 v[208:211], v181 offset:33792
	ds_read_b128 v[212:215], v181 offset:34816
	ds_read_b128 v[216:219], v181 offset:35840
	ds_read_b128 v[220:223], v181 offset:36864
	ds_read_b128 v[224:227], v181 offset:37888
	ds_read_b128 v[228:231], v181 offset:38912
	ds_read_b128 v[232:235], v181 offset:39936
	global_load_lds_dwordx4 v134, s[54:55]
	s_mov_b32 m0, s23
	s_nop 0
	global_load_lds_dwordx4 v132, s[54:55]
	s_waitcnt vmcnt(8)
	s_waitcnt lgkmcnt(0)
	s_setprio 1
	s_barrier
	v_mfma_f32_16x16x32_bf16 v[126:129], v[140:143], v[204:207], v[126:129]
	v_mfma_f32_16x16x32_bf16 v[122:125], v[148:151], v[204:207], v[122:125]
	v_mfma_f32_16x16x32_bf16 v[118:121], v[140:143], v[212:215], v[118:121]
	v_mfma_f32_16x16x32_bf16 v[114:117], v[148:151], v[212:215], v[114:117]
	v_mfma_f32_16x16x32_bf16 v[106:109], v[140:143], v[220:223], v[106:109]
	v_mfma_f32_16x16x32_bf16 v[98:101], v[148:151], v[220:223], v[98:101]
	v_mfma_f32_16x16x32_bf16 v[90:93], v[140:143], v[228:231], v[90:93]
	v_mfma_f32_16x16x32_bf16 v[82:85], v[148:151], v[228:231], v[82:85]
	v_mfma_f32_16x16x32_bf16 v[126:129], v[144:147], v[208:211], v[126:129]
	v_mfma_f32_16x16x32_bf16 v[122:125], v[152:155], v[208:211], v[122:125]
	v_mfma_f32_16x16x32_bf16 v[118:121], v[144:147], v[216:219], v[118:121]
	v_mfma_f32_16x16x32_bf16 v[114:117], v[152:155], v[216:219], v[114:117]
	v_mfma_f32_16x16x32_bf16 v[106:109], v[144:147], v[224:227], v[106:109]
	v_mfma_f32_16x16x32_bf16 v[98:101], v[152:155], v[224:227], v[98:101]
	v_mfma_f32_16x16x32_bf16 v[90:93], v[144:147], v[232:235], v[90:93]
	v_mfma_f32_16x16x32_bf16 v[82:85], v[152:155], v[232:235], v[82:85]
	v_mfma_f32_16x16x32_bf16 v[110:113], v[184:187], v[204:207], v[110:113]
	v_mfma_f32_16x16x32_bf16 v[102:105], v[192:195], v[204:207], v[102:105]
	v_mfma_f32_16x16x32_bf16 v[94:97], v[184:187], v[212:215], v[94:97]
	v_mfma_f32_16x16x32_bf16 v[86:89], v[192:195], v[212:215], v[86:89]
	v_mfma_f32_16x16x32_bf16 v[78:81], v[184:187], v[220:223], v[78:81]
	v_mfma_f32_16x16x32_bf16 v[74:77], v[192:195], v[220:223], v[74:77]
	v_mfma_f32_16x16x32_bf16 v[70:73], v[184:187], v[228:231], v[70:73]
	v_mfma_f32_16x16x32_bf16 v[66:69], v[192:195], v[228:231], v[66:69]
	v_mfma_f32_16x16x32_bf16 v[110:113], v[188:191], v[208:211], v[110:113]
	v_mfma_f32_16x16x32_bf16 v[102:105], v[196:199], v[208:211], v[102:105]
	v_mfma_f32_16x16x32_bf16 v[94:97], v[188:191], v[216:219], v[94:97]
	v_mfma_f32_16x16x32_bf16 v[86:89], v[196:199], v[216:219], v[86:89]
	v_mfma_f32_16x16x32_bf16 v[78:81], v[188:191], v[224:227], v[78:81]
	v_mfma_f32_16x16x32_bf16 v[74:77], v[196:199], v[224:227], v[74:77]
	v_mfma_f32_16x16x32_bf16 v[70:73], v[188:191], v[232:235], v[70:73]
	v_mfma_f32_16x16x32_bf16 v[66:69], v[196:199], v[232:235], v[66:69]
	s_barrier
	s_setprio 0
	s_add_i32 s29, s29, s4
	v_lshl_add_u64 v[170:171], v[170:171], 0, s[24:25]
	s_mov_b32 m0, s29
	ds_read_b128 v[204:207], v181 offset:49152
	ds_read_b128 v[208:211], v181 offset:50176
	ds_read_b128 v[212:215], v181 offset:51200
	ds_read_b128 v[216:219], v181 offset:52224
	ds_read_b128 v[220:223], v181 offset:53248
	ds_read_b128 v[224:227], v181 offset:54272
	ds_read_b128 v[228:231], v181 offset:55296
	ds_read_b128 v[232:235], v181 offset:56320
	global_load_lds_dwordx4 v[170:171], off
	s_add_i32 m0, s29, 0x2000
	s_add_u32 s52, s52, 0x40080
	v_lshl_add_u64 v[170:171], v[172:173], 0, s[24:25]
	s_addc_u32 s53, s53, 0
	s_add_i32 s29, s37, s4
	global_load_lds_dwordx4 v[170:171], off
	s_mov_b32 m0, s29
	s_nop 0
	global_load_lds_dwordx4 v0, s[52:53]
	s_add_i32 m0, s29, 0x2000
	s_nop 0
	global_load_lds_dwordx4 v130, s[52:53]
	v_lshl_add_u64 v[170:171], v[236:237], 0, s[24:25]
	s_mov_b32 m0, s31
	s_nop 0
	global_load_lds_dwordx4 v[170:171], off
	v_lshl_add_u64 v[170:171], v[238:239], 0, s[24:25]
	s_mov_b32 m0, s33
	s_nop 0
	global_load_lds_dwordx4 v[170:171], off
	s_waitcnt vmcnt(8)
	s_waitcnt lgkmcnt(0)
	s_setprio 1
	s_barrier
	v_mfma_f32_16x16x32_bf16 v[62:65], v[140:143], v[204:207], v[62:65]
	v_mfma_f32_16x16x32_bf16 v[58:61], v[148:151], v[204:207], v[58:61]
	v_mfma_f32_16x16x32_bf16 v[54:57], v[140:143], v[212:215], v[54:57]
	v_mfma_f32_16x16x32_bf16 v[50:53], v[148:151], v[212:215], v[50:53]
	v_mfma_f32_16x16x32_bf16 v[42:45], v[140:143], v[220:223], v[42:45]
	v_mfma_f32_16x16x32_bf16 v[34:37], v[148:151], v[220:223], v[34:37]
	v_mfma_f32_16x16x32_bf16 v[26:29], v[140:143], v[228:231], v[26:29]
	v_mfma_f32_16x16x32_bf16 v[18:21], v[148:151], v[228:231], v[18:21]
	v_mfma_f32_16x16x32_bf16 v[62:65], v[144:147], v[208:211], v[62:65]
	v_mfma_f32_16x16x32_bf16 v[58:61], v[152:155], v[208:211], v[58:61]
	v_mfma_f32_16x16x32_bf16 v[54:57], v[144:147], v[216:219], v[54:57]
	v_mfma_f32_16x16x32_bf16 v[50:53], v[152:155], v[216:219], v[50:53]
	v_mfma_f32_16x16x32_bf16 v[42:45], v[144:147], v[224:227], v[42:45]
	v_mfma_f32_16x16x32_bf16 v[34:37], v[152:155], v[224:227], v[34:37]
	v_mfma_f32_16x16x32_bf16 v[26:29], v[144:147], v[232:235], v[26:29]
	v_mfma_f32_16x16x32_bf16 v[18:21], v[152:155], v[232:235], v[18:21]
	v_mfma_f32_16x16x32_bf16 v[46:49], v[184:187], v[204:207], v[46:49]
	v_mfma_f32_16x16x32_bf16 v[38:41], v[192:195], v[204:207], v[38:41]
	v_mfma_f32_16x16x32_bf16 v[30:33], v[184:187], v[212:215], v[30:33]
	v_mfma_f32_16x16x32_bf16 v[22:25], v[192:195], v[212:215], v[22:25]
	v_mfma_f32_16x16x32_bf16 v[14:17], v[184:187], v[220:223], v[14:17]
	v_mfma_f32_16x16x32_bf16 v[10:13], v[192:195], v[220:223], v[10:13]
	v_mfma_f32_16x16x32_bf16 v[6:9], v[184:187], v[228:231], v[6:9]
	v_mfma_f32_16x16x32_bf16 v[2:5], v[192:195], v[228:231], v[2:5]
	v_mfma_f32_16x16x32_bf16 v[46:49], v[188:191], v[208:211], v[46:49]
	v_mfma_f32_16x16x32_bf16 v[38:41], v[196:199], v[208:211], v[38:41]
	v_mfma_f32_16x16x32_bf16 v[30:33], v[188:191], v[216:219], v[30:33]
	v_mfma_f32_16x16x32_bf16 v[22:25], v[196:199], v[216:219], v[22:25]
	v_mfma_f32_16x16x32_bf16 v[14:17], v[188:191], v[224:227], v[14:17]
	v_mfma_f32_16x16x32_bf16 v[10:13], v[196:199], v[224:227], v[10:13]
	v_mfma_f32_16x16x32_bf16 v[6:9], v[188:191], v[232:235], v[6:9]
	v_mfma_f32_16x16x32_bf16 v[2:5], v[196:199], v[232:235], v[2:5]
	s_barrier
	s_setprio 0
	s_add_u32 s16, s16, 0x100
	s_addc_u32 s17, s17, 0
	s_add_u32 s38, s38, 0x100
	s_addc_u32 s39, s39, 0
	s_cmp_ge_i32 s56, s3
	s_mov_b32 s52, s56
	s_cbranch_scc0 .LBB7_1219
	s_branch .Lpeelx_1219

.Lpeelx_1219:
	v_pk_mul_f32 v[128:129], v[128:129], s[36:37] op_sel_hi:[1,0]
	v_pk_mul_f32 v[144:145], v[126:127], s[36:37] op_sel_hi:[1,0]
	v_pk_mul_f32 v[126:127], v[124:125], s[36:37] op_sel_hi:[1,0]
	v_pk_mul_f32 v[140:141], v[122:123], s[36:37] op_sel_hi:[1,0]
	v_pk_mul_f32 v[146:147], v[112:113], s[36:37] op_sel_hi:[1,0]
	v_pk_mul_f32 v[150:151], v[110:111], s[36:37] op_sel_hi:[1,0]
	v_pk_mul_f32 v[142:143], v[104:105], s[36:37] op_sel_hi:[1,0]
	v_pk_mul_f32 v[148:149], v[102:103], s[36:37] op_sel_hi:[1,0]
	v_pk_mul_f32 v[120:121], v[120:121], s[36:37] op_sel_hi:[1,0]
	v_pk_mul_f32 v[118:119], v[118:119], s[36:37] op_sel_hi:[1,0]
	v_pk_mul_f32 v[110:111], v[116:117], s[36:37] op_sel_hi:[1,0]
	v_pk_mul_f32 v[112:113], v[114:115], s[36:37] op_sel_hi:[1,0]
	v_pk_mul_f32 v[116:117], v[96:97], s[36:37] op_sel_hi:[1,0]
	v_pk_mul_f32 v[124:125], v[94:95], s[36:37] op_sel_hi:[1,0]
	v_pk_mul_f32 v[114:115], v[88:89], s[36:37] op_sel_hi:[1,0]
	v_pk_mul_f32 v[122:123], v[86:87], s[36:37] op_sel_hi:[1,0]
	v_pk_mul_f32 v[102:103], v[108:109], s[36:37] op_sel_hi:[1,0]
	v_pk_mul_f32 v[104:105], v[106:107], s[36:37] op_sel_hi:[1,0]
	v_pk_mul_f32 v[94:95], v[100:101], s[36:37] op_sel_hi:[1,0]
	v_pk_mul_f32 v[96:97], v[98:99], s[36:37] op_sel_hi:[1,0]
	v_pk_mul_f32 v[100:101], v[80:81], s[36:37] op_sel_hi:[1,0]
	v_pk_mul_f32 v[108:109], v[78:79], s[36:37] op_sel_hi:[1,0]
	v_pk_mul_f32 v[98:99], v[76:77], s[36:37] op_sel_hi:[1,0]
	v_pk_mul_f32 v[106:107], v[74:75], s[36:37] op_sel_hi:[1,0]
	v_pk_mul_f32 v[86:87], v[92:93], s[36:37] op_sel_hi:[1,0]
	v_pk_mul_f32 v[88:89], v[90:91], s[36:37] op_sel_hi:[1,0]
	v_pk_mul_f32 v[76:77], v[84:85], s[36:37] op_sel_hi:[1,0]
	v_pk_mul_f32 v[80:81], v[82:83], s[36:37] op_sel_hi:[1,0]
	v_pk_mul_f32 v[84:85], v[72:73], s[36:37] op_sel_hi:[1,0]
	v_pk_mul_f32 v[92:93], v[70:71], s[36:37] op_sel_hi:[1,0]
	v_pk_mul_f32 v[82:83], v[68:69], s[36:37] op_sel_hi:[1,0]
	v_pk_mul_f32 v[90:91], v[66:67], s[36:37] op_sel_hi:[1,0]
	v_pk_mul_f32 v[66:67], v[64:65], s[36:37] op_sel_hi:[1,0]
	v_pk_mul_f32 v[72:73], v[62:63], s[36:37] op_sel_hi:[1,0]
	v_pk_mul_f32 v[62:63], v[60:61], s[36:37] op_sel_hi:[1,0]
	v_pk_mul_f32 v[64:65], v[58:59], s[36:37] op_sel_hi:[1,0]
	v_pk_mul_f32 v[70:71], v[48:49], s[36:37] op_sel_hi:[1,0]
	v_pk_mul_f32 v[78:79], v[46:47], s[36:37] op_sel_hi:[1,0]
	v_pk_mul_f32 v[68:69], v[40:41], s[36:37] op_sel_hi:[1,0]
	v_pk_mul_f32 v[74:75], v[38:39], s[36:37] op_sel_hi:[1,0]
	v_pk_mul_f32 v[56:57], v[56:57], s[36:37] op_sel_hi:[1,0]
	v_pk_mul_f32 v[54:55], v[54:55], s[36:37] op_sel_hi:[1,0]
	v_pk_mul_f32 v[46:47], v[52:53], s[36:37] op_sel_hi:[1,0]
	v_pk_mul_f32 v[48:49], v[50:51], s[36:37] op_sel_hi:[1,0]
	v_pk_mul_f32 v[52:53], v[32:33], s[36:37] op_sel_hi:[1,0]
	v_pk_mul_f32 v[60:61], v[30:31], s[36:37] op_sel_hi:[1,0]
	v_pk_mul_f32 v[50:51], v[24:25], s[36:37] op_sel_hi:[1,0]
	v_pk_mul_f32 v[58:59], v[22:23], s[36:37] op_sel_hi:[1,0]
	v_pk_mul_f32 v[30:31], v[44:45], s[36:37] op_sel_hi:[1,0]
	v_pk_mul_f32 v[38:39], v[42:43], s[36:37] op_sel_hi:[1,0]
	v_pk_mul_f32 v[22:23], v[36:37], s[36:37] op_sel_hi:[1,0]
	v_pk_mul_f32 v[24:25], v[34:35], s[36:37] op_sel_hi:[1,0]
	v_pk_mul_f32 v[34:35], v[16:17], s[36:37] op_sel_hi:[1,0]
	v_pk_mul_f32 v[40:41], v[14:15], s[36:37] op_sel_hi:[1,0]
	v_pk_mul_f32 v[32:33], v[12:13], s[36:37] op_sel_hi:[1,0]
	v_pk_mul_f32 v[36:37], v[10:11], s[36:37] op_sel_hi:[1,0]
	v_pk_mul_f32 v[14:15], v[28:29], s[36:37] op_sel_hi:[1,0]
	v_pk_mul_f32 v[16:17], v[26:27], s[36:37] op_sel_hi:[1,0]
	v_pk_mul_f32 v[10:11], v[20:21], s[36:37] op_sel_hi:[1,0]
	v_pk_mul_f32 v[12:13], v[18:19], s[36:37] op_sel_hi:[1,0]
	v_pk_mul_f32 v[8:9], v[8:9], s[36:37] op_sel_hi:[1,0]
	v_pk_mul_f32 v[6:7], v[6:7], s[36:37] op_sel_hi:[1,0]
	v_pk_mul_f32 v[4:5], v[4:5], s[36:37] op_sel_hi:[1,0]
	v_pk_mul_f32 v[2:3], v[2:3], s[36:37] op_sel_hi:[1,0]
	s_mov_b32 s56, s61
	s_and_b64 vcc, exec, s[6:7]
	s_cbranch_vccz .LBB7_1222

.LBB7_1272:
	s_add_u32 s42, s64, s16
	s_addc_u32 s43, s65, s17
	v_readlane_b32 s13, v254, 40
	s_add_u32 s44, s13, s18
	v_readlane_b32 s13, v254, 41
	s_addc_u32 s45, s13, s19
	s_andn2_b64 vcc, exec, s[8:9]
	s_cbranch_vccnz .LBB7_1280
	s_and_b64 s[52:53], s[40:41], exec
	s_cselect_b32 s13, s43, s49
	s_cselect_b32 s15, s42, s48
	s_cselect_b32 s54, s45, s51
	s_cselect_b32 s55, s44, s50
	s_add_u32 s48, s48, 0x40080
	s_addc_u32 s49, s49, 0
	s_add_u32 s56, s50, 0x100
	s_addc_u32 s57, s51, 0
	s_mov_b32 s50, 0
.Lpeel_1274:
	s_add_i32 s72, s50, 2
	s_add_u32 s29, s48, 0xfffc0080
	s_addc_u32 s37, s49, -1
	s_add_i32 s73, 0, 0x10000
	s_cmp_eq_u32 s33, s50
	s_cselect_b32 s53, s13, s37
	s_cselect_b32 s52, s15, s29
	s_cselect_b32 s51, s54, s57
	s_cselect_b32 s50, s55, s56
	s_add_i32 s29, 0, 0x14000
	v_add_u32_e32 v156, s73, v141
	v_add_u32_e32 v160, s29, v141
	ds_read_b128 v[144:147], v156
	ds_read_b128 v[148:151], v156 offset:1024
	ds_read_b128 v[152:155], v156 offset:2048
	ds_read_b128 v[156:159], v156 offset:3072
	ds_read_b128 v[174:177], v160
	ds_read_b128 v[178:181], v160 offset:1024
	ds_read_b128 v[182:185], v160 offset:2048
	ds_read_b128 v[186:189], v160 offset:3072
	s_add_i32 m0, s5, 0xc000
	ds_read_b128 v[190:193], v143
	ds_read_b128 v[194:197], v143 offset:1024
	ds_read_b128 v[204:207], v143 offset:2048
	ds_read_b128 v[208:211], v143 offset:3072
	ds_read_b128 v[212:215], v143 offset:4096
	ds_read_b128 v[216:219], v143 offset:5120
	ds_read_b128 v[220:223], v143 offset:6144
	ds_read_b128 v[224:227], v143 offset:7168
	global_load_lds_dwordx4 v136, s[48:49]
	s_add_i32 m0, s5, 0xe000
	s_nop 0
	global_load_lds_dwordx4 v138, s[48:49]
	s_waitcnt vmcnt(8)
	s_waitcnt lgkmcnt(0)
	s_setprio 1
	s_barrier
	v_mfma_f32_16x16x32_bf16 v[126:129], v[144:147], v[190:193], 0
	v_mfma_f32_16x16x32_bf16 v[122:125], v[152:155], v[190:193], 0
	v_mfma_f32_16x16x32_bf16 v[110:113], v[144:147], v[204:207], 0
	v_mfma_f32_16x16x32_bf16 v[106:109], v[152:155], v[204:207], 0
	v_mfma_f32_16x16x32_bf16 v[94:97], v[144:147], v[212:215], 0
	v_mfma_f32_16x16x32_bf16 v[90:93], v[152:155], v[212:215], 0
	v_mfma_f32_16x16x32_bf16 v[78:81], v[144:147], v[220:223], 0
	v_mfma_f32_16x16x32_bf16 v[74:77], v[152:155], v[220:223], 0
	v_mfma_f32_16x16x32_bf16 v[126:129], v[148:151], v[194:197], v[126:129]
	v_mfma_f32_16x16x32_bf16 v[122:125], v[156:159], v[194:197], v[122:125]
	v_mfma_f32_16x16x32_bf16 v[110:113], v[148:151], v[208:211], v[110:113]
	v_mfma_f32_16x16x32_bf16 v[106:109], v[156:159], v[208:211], v[106:109]
	v_mfma_f32_16x16x32_bf16 v[94:97], v[148:151], v[216:219], v[94:97]
	v_mfma_f32_16x16x32_bf16 v[90:93], v[156:159], v[216:219], v[90:93]
	v_mfma_f32_16x16x32_bf16 v[78:81], v[148:151], v[224:227], v[78:81]
	v_mfma_f32_16x16x32_bf16 v[74:77], v[156:159], v[224:227], v[74:77]
	v_mfma_f32_16x16x32_bf16 v[118:121], v[174:177], v[190:193], 0
	v_mfma_f32_16x16x32_bf16 v[114:117], v[182:185], v[190:193], 0
	v_mfma_f32_16x16x32_bf16 v[102:105], v[174:177], v[204:207], 0
	v_mfma_f32_16x16x32_bf16 v[98:101], v[182:185], v[204:207], 0
	v_mfma_f32_16x16x32_bf16 v[86:89], v[174:177], v[212:215], 0
	v_mfma_f32_16x16x32_bf16 v[82:85], v[182:185], v[212:215], 0
	v_mfma_f32_16x16x32_bf16 v[70:73], v[174:177], v[220:223], 0
	v_mfma_f32_16x16x32_bf16 v[66:69], v[182:185], v[220:223], 0
	v_mfma_f32_16x16x32_bf16 v[118:121], v[178:181], v[194:197], v[118:121]
	v_mfma_f32_16x16x32_bf16 v[114:117], v[186:189], v[194:197], v[114:117]
	v_mfma_f32_16x16x32_bf16 v[102:105], v[178:181], v[208:211], v[102:105]
	v_mfma_f32_16x16x32_bf16 v[98:101], v[186:189], v[208:211], v[98:101]
	v_mfma_f32_16x16x32_bf16 v[86:89], v[178:181], v[216:219], v[86:89]
	v_mfma_f32_16x16x32_bf16 v[82:85], v[186:189], v[216:219], v[82:85]
	v_mfma_f32_16x16x32_bf16 v[70:73], v[178:181], v[224:227], v[70:73]
	v_mfma_f32_16x16x32_bf16 v[66:69], v[186:189], v[224:227], v[66:69]
	s_barrier
	s_setprio 0
	s_add_i32 s37, s73, s4
	v_lshl_add_u64 v[160:161], s[50:51], 0, v[0:1]
	s_mov_b32 m0, s37
	ds_read_b128 v[190:193], v143 offset:16384
	ds_read_b128 v[194:197], v143 offset:17408
	ds_read_b128 v[204:207], v143 offset:18432
	ds_read_b128 v[208:211], v143 offset:19456
	ds_read_b128 v[212:215], v143 offset:20480
	ds_read_b128 v[216:219], v143 offset:21504
	ds_read_b128 v[220:223], v143 offset:22528
	ds_read_b128 v[224:227], v143 offset:23552
	global_load_lds_dwordx4 v[160:161], off
	s_add_i32 m0, s37, 0x2000
	s_add_u32 s74, s50, 0x100000
	v_lshl_add_u64 v[170:171], s[50:51], 0, v[130:131]
	s_addc_u32 s75, s51, 0
	s_add_i32 s29, s29, s4
	global_load_lds_dwordx4 v[170:171], off
	s_mov_b32 m0, s29
	v_lshl_add_u64 v[198:199], s[52:53], 0, v[132:133]
	global_load_lds_dwordx4 v0, s[74:75]
	s_add_i32 m0, s29, 0x2000
	s_nop 0
	global_load_lds_dwordx4 v130, s[74:75]
	v_lshl_add_u64 v[172:173], s[52:53], 0, v[134:135]
	s_mov_b32 m0, s5
	s_nop 0
	global_load_lds_dwordx4 v[172:173], off
	s_mov_b32 m0, s10
	s_nop 0
	global_load_lds_dwordx4 v[198:199], off
	s_waitcnt vmcnt(8)
	s_waitcnt lgkmcnt(0)
	s_setprio 1
	s_barrier
	v_mfma_f32_16x16x32_bf16 v[62:65], v[144:147], v[190:193], 0
	v_mfma_f32_16x16x32_bf16 v[58:61], v[152:155], v[190:193], 0
	v_mfma_f32_16x16x32_bf16 v[46:49], v[144:147], v[204:207], 0
	v_mfma_f32_16x16x32_bf16 v[42:45], v[152:155], v[204:207], 0
	v_mfma_f32_16x16x32_bf16 v[30:33], v[144:147], v[212:215], 0
	v_mfma_f32_16x16x32_bf16 v[26:29], v[152:155], v[212:215], 0
	v_mfma_f32_16x16x32_bf16 v[14:17], v[144:147], v[220:223], 0
	v_mfma_f32_16x16x32_bf16 v[10:13], v[152:155], v[220:223], 0
	v_mfma_f32_16x16x32_bf16 v[62:65], v[148:151], v[194:197], v[62:65]
	v_mfma_f32_16x16x32_bf16 v[58:61], v[156:159], v[194:197], v[58:61]
	v_mfma_f32_16x16x32_bf16 v[46:49], v[148:151], v[208:211], v[46:49]
	v_mfma_f32_16x16x32_bf16 v[42:45], v[156:159], v[208:211], v[42:45]
	v_mfma_f32_16x16x32_bf16 v[30:33], v[148:151], v[216:219], v[30:33]
	v_mfma_f32_16x16x32_bf16 v[26:29], v[156:159], v[216:219], v[26:29]
	v_mfma_f32_16x16x32_bf16 v[14:17], v[148:151], v[224:227], v[14:17]
	v_mfma_f32_16x16x32_bf16 v[10:13], v[156:159], v[224:227], v[10:13]
	v_mfma_f32_16x16x32_bf16 v[54:57], v[174:177], v[190:193], 0
	v_mfma_f32_16x16x32_bf16 v[50:53], v[182:185], v[190:193], 0
	v_mfma_f32_16x16x32_bf16 v[38:41], v[174:177], v[204:207], 0
	v_mfma_f32_16x16x32_bf16 v[34:37], v[182:185], v[204:207], 0
	v_mfma_f32_16x16x32_bf16 v[22:25], v[174:177], v[212:215], 0
	v_mfma_f32_16x16x32_bf16 v[18:21], v[182:185], v[212:215], 0
	v_mfma_f32_16x16x32_bf16 v[6:9], v[174:177], v[220:223], 0
	v_mfma_f32_16x16x32_bf16 v[2:5], v[182:185], v[220:223], 0
	v_mfma_f32_16x16x32_bf16 v[54:57], v[178:181], v[194:197], v[54:57]
	v_mfma_f32_16x16x32_bf16 v[50:53], v[186:189], v[194:197], v[50:53]
	v_mfma_f32_16x16x32_bf16 v[38:41], v[178:181], v[208:211], v[38:41]
	v_mfma_f32_16x16x32_bf16 v[34:37], v[186:189], v[208:211], v[34:37]
	v_mfma_f32_16x16x32_bf16 v[22:25], v[178:181], v[216:219], v[22:25]
	v_mfma_f32_16x16x32_bf16 v[18:21], v[186:189], v[216:219], v[18:21]
	v_mfma_f32_16x16x32_bf16 v[6:9], v[178:181], v[224:227], v[6:9]
	v_mfma_f32_16x16x32_bf16 v[2:5], v[186:189], v[224:227], v[2:5]
	s_barrier
	s_setprio 0
	s_add_i32 s29, 0, 0x18000
	s_add_i32 s37, 0, 0x1c000
	v_add_u32_e32 v156, s29, v141
	v_add_u32_e32 v186, s37, v141
	ds_read_b128 v[144:147], v156
	ds_read_b128 v[148:151], v156 offset:1024
	ds_read_b128 v[152:155], v156 offset:2048
	ds_read_b128 v[156:159], v156 offset:3072
	ds_read_b128 v[174:177], v186
	ds_read_b128 v[178:181], v186 offset:1024
	ds_read_b128 v[182:185], v186 offset:2048
	ds_read_b128 v[186:189], v186 offset:3072
	s_add_u32 s52, s52, 0x40000
	s_addc_u32 s53, s53, 0
	s_mov_b32 m0, s20
	ds_read_b128 v[190:193], v143 offset:32768
	ds_read_b128 v[194:197], v143 offset:33792
	ds_read_b128 v[204:207], v143 offset:34816
	ds_read_b128 v[208:211], v143 offset:35840
	ds_read_b128 v[212:215], v143 offset:36864
	ds_read_b128 v[216:219], v143 offset:37888
	ds_read_b128 v[220:223], v143 offset:38912
	ds_read_b128 v[224:227], v143 offset:39936
	global_load_lds_dwordx4 v134, s[52:53]
	s_mov_b32 m0, s22
	s_nop 0
	global_load_lds_dwordx4 v132, s[52:53]
	s_waitcnt vmcnt(8)
	s_waitcnt lgkmcnt(0)
	s_setprio 1
	s_barrier
	v_mfma_f32_16x16x32_bf16 v[126:129], v[144:147], v[190:193], v[126:129]
	v_mfma_f32_16x16x32_bf16 v[122:125], v[152:155], v[190:193], v[122:125]
	v_mfma_f32_16x16x32_bf16 v[110:113], v[144:147], v[204:207], v[110:113]
	v_mfma_f32_16x16x32_bf16 v[106:109], v[152:155], v[204:207], v[106:109]
	v_mfma_f32_16x16x32_bf16 v[94:97], v[144:147], v[212:215], v[94:97]
	v_mfma_f32_16x16x32_bf16 v[90:93], v[152:155], v[212:215], v[90:93]
	v_mfma_f32_16x16x32_bf16 v[78:81], v[144:147], v[220:223], v[78:81]
	v_mfma_f32_16x16x32_bf16 v[74:77], v[152:155], v[220:223], v[74:77]
	v_mfma_f32_16x16x32_bf16 v[126:129], v[148:151], v[194:197], v[126:129]
	v_mfma_f32_16x16x32_bf16 v[122:125], v[156:159], v[194:197], v[122:125]
	v_mfma_f32_16x16x32_bf16 v[110:113], v[148:151], v[208:211], v[110:113]
	v_mfma_f32_16x16x32_bf16 v[106:109], v[156:159], v[208:211], v[106:109]
	v_mfma_f32_16x16x32_bf16 v[94:97], v[148:151], v[216:219], v[94:97]
	v_mfma_f32_16x16x32_bf16 v[90:93], v[156:159], v[216:219], v[90:93]
	v_mfma_f32_16x16x32_bf16 v[78:81], v[148:151], v[224:227], v[78:81]
	v_mfma_f32_16x16x32_bf16 v[74:77], v[156:159], v[224:227], v[74:77]
	v_mfma_f32_16x16x32_bf16 v[118:121], v[174:177], v[190:193], v[118:121]
	v_mfma_f32_16x16x32_bf16 v[114:117], v[182:185], v[190:193], v[114:117]
	v_mfma_f32_16x16x32_bf16 v[102:105], v[174:177], v[204:207], v[102:105]
	v_mfma_f32_16x16x32_bf16 v[98:101], v[182:185], v[204:207], v[98:101]
	v_mfma_f32_16x16x32_bf16 v[86:89], v[174:177], v[212:215], v[86:89]
	v_mfma_f32_16x16x32_bf16 v[82:85], v[182:185], v[212:215], v[82:85]
	v_mfma_f32_16x16x32_bf16 v[70:73], v[174:177], v[220:223], v[70:73]
	v_mfma_f32_16x16x32_bf16 v[66:69], v[182:185], v[220:223], v[66:69]
	v_mfma_f32_16x16x32_bf16 v[118:121], v[178:181], v[194:197], v[118:121]
	v_mfma_f32_16x16x32_bf16 v[114:117], v[186:189], v[194:197], v[114:117]
	v_mfma_f32_16x16x32_bf16 v[102:105], v[178:181], v[208:211], v[102:105]
	v_mfma_f32_16x16x32_bf16 v[98:101], v[186:189], v[208:211], v[98:101]
	v_mfma_f32_16x16x32_bf16 v[86:89], v[178:181], v[216:219], v[86:89]
	v_mfma_f32_16x16x32_bf16 v[82:85], v[186:189], v[216:219], v[82:85]
	v_mfma_f32_16x16x32_bf16 v[70:73], v[178:181], v[224:227], v[70:73]
	v_mfma_f32_16x16x32_bf16 v[66:69], v[186:189], v[224:227], v[66:69]
	s_barrier
	s_setprio 0
	s_add_i32 s29, s29, s4
	v_lshl_add_u64 v[160:161], v[160:161], 0, s[24:25]
	s_mov_b32 m0, s29
	ds_read_b128 v[190:193], v143 offset:49152
	ds_read_b128 v[194:197], v143 offset:50176
	ds_read_b128 v[204:207], v143 offset:51200
	ds_read_b128 v[208:211], v143 offset:52224
	ds_read_b128 v[212:215], v143 offset:53248
	ds_read_b128 v[216:219], v143 offset:54272
	ds_read_b128 v[220:223], v143 offset:55296
	ds_read_b128 v[224:227], v143 offset:56320
	global_load_lds_dwordx4 v[160:161], off
	s_add_i32 m0, s29, 0x2000
	s_add_u32 s50, s50, 0x100080
	v_lshl_add_u64 v[160:161], v[170:171], 0, s[24:25]
	s_addc_u32 s51, s51, 0
	s_add_i32 s29, s37, s4
	global_load_lds_dwordx4 v[160:161], off
	s_mov_b32 m0, s29
	s_nop 0
	global_load_lds_dwordx4 v0, s[50:51]
	s_add_i32 m0, s29, 0x2000
	s_nop 0
	global_load_lds_dwordx4 v130, s[50:51]
	v_lshl_add_u64 v[160:161], v[172:173], 0, s[24:25]
	s_mov_b32 m0, s23
	s_nop 0
	global_load_lds_dwordx4 v[160:161], off
	v_lshl_add_u64 v[160:161], v[198:199], 0, s[24:25]
	s_mov_b32 m0, s28
	s_nop 0
	global_load_lds_dwordx4 v[160:161], off
	s_waitcnt vmcnt(8)
	s_waitcnt lgkmcnt(0)
	s_setprio 1
	s_barrier
	v_mfma_f32_16x16x32_bf16 v[62:65], v[144:147], v[190:193], v[62:65]
	v_mfma_f32_16x16x32_bf16 v[58:61], v[152:155], v[190:193], v[58:61]
	v_mfma_f32_16x16x32_bf16 v[46:49], v[144:147], v[204:207], v[46:49]
	v_mfma_f32_16x16x32_bf16 v[42:45], v[152:155], v[204:207], v[42:45]
	v_mfma_f32_16x16x32_bf16 v[30:33], v[144:147], v[212:215], v[30:33]
	v_mfma_f32_16x16x32_bf16 v[26:29], v[152:155], v[212:215], v[26:29]
	v_mfma_f32_16x16x32_bf16 v[14:17], v[144:147], v[220:223], v[14:17]
	v_mfma_f32_16x16x32_bf16 v[10:13], v[152:155], v[220:223], v[10:13]
	v_mfma_f32_16x16x32_bf16 v[62:65], v[148:151], v[194:197], v[62:65]
	v_mfma_f32_16x16x32_bf16 v[58:61], v[156:159], v[194:197], v[58:61]
	v_mfma_f32_16x16x32_bf16 v[46:49], v[148:151], v[208:211], v[46:49]
	v_mfma_f32_16x16x32_bf16 v[42:45], v[156:159], v[208:211], v[42:45]
	v_mfma_f32_16x16x32_bf16 v[30:33], v[148:151], v[216:219], v[30:33]
	v_mfma_f32_16x16x32_bf16 v[26:29], v[156:159], v[216:219], v[26:29]
	v_mfma_f32_16x16x32_bf16 v[14:17], v[148:151], v[224:227], v[14:17]
	v_mfma_f32_16x16x32_bf16 v[10:13], v[156:159], v[224:227], v[10:13]
	v_mfma_f32_16x16x32_bf16 v[54:57], v[174:177], v[190:193], v[54:57]
	v_mfma_f32_16x16x32_bf16 v[50:53], v[182:185], v[190:193], v[50:53]
	v_mfma_f32_16x16x32_bf16 v[38:41], v[174:177], v[204:207], v[38:41]
	v_mfma_f32_16x16x32_bf16 v[34:37], v[182:185], v[204:207], v[34:37]
	v_mfma_f32_16x16x32_bf16 v[22:25], v[174:177], v[212:215], v[22:25]
	v_mfma_f32_16x16x32_bf16 v[18:21], v[182:185], v[212:215], v[18:21]
	v_mfma_f32_16x16x32_bf16 v[6:9], v[174:177], v[220:223], v[6:9]
	v_mfma_f32_16x16x32_bf16 v[2:5], v[182:185], v[220:223], v[2:5]
	v_mfma_f32_16x16x32_bf16 v[54:57], v[178:181], v[194:197], v[54:57]
	v_mfma_f32_16x16x32_bf16 v[50:53], v[186:189], v[194:197], v[50:53]
	v_mfma_f32_16x16x32_bf16 v[38:41], v[178:181], v[208:211], v[38:41]
	v_mfma_f32_16x16x32_bf16 v[34:37], v[186:189], v[208:211], v[34:37]
	v_mfma_f32_16x16x32_bf16 v[22:25], v[178:181], v[216:219], v[22:25]
	v_mfma_f32_16x16x32_bf16 v[18:21], v[186:189], v[216:219], v[18:21]
	v_mfma_f32_16x16x32_bf16 v[6:9], v[178:181], v[224:227], v[6:9]
	v_mfma_f32_16x16x32_bf16 v[2:5], v[186:189], v[224:227], v[2:5]
	s_barrier
	s_setprio 0
	s_add_u32 s48, s48, 0x100
	s_addc_u32 s49, s49, 0
	s_add_u32 s56, s56, 0x100
	s_addc_u32 s57, s57, 0
	s_cmp_ge_i32 s72, s3
	s_mov_b32 s50, s72
	s_cbranch_scc0 .LBB7_1274
	s_branch .Lpeelx_1274
